# P0 adaLN GEMV main loop software-pipelined (16 loads in flight), on top of v15
# baseline (speedup 1.0000x reference)
.LBB0_30:
	v_lshl_add_u64 v[84:85], v[30:31], 0, v[28:29]
	v_add_co_u32_e64 v56, s[0:1], s15, v84
	s_nop 1
	v_addc_co_u32_e64 v57, s[0:1], -1, v85, s[0:1]
	v_add_co_u32_e64 v60, s[0:1], s24, v84
	s_nop 1
	v_addc_co_u32_e64 v61, s[0:1], -1, v85, s[0:1]
	v_add_co_u32_e64 v64, s[0:1], s25, v84
	s_nop 1
	v_addc_co_u32_e64 v65, s[0:1], -1, v85, s[0:1]
	v_add_co_u32_e64 v68, s[0:1], s26, v84
	s_nop 1
	v_addc_co_u32_e64 v69, s[0:1], -1, v85, s[0:1]
	v_add_co_u32_e64 v72, s[0:1], s27, v84
	s_nop 1
	v_addc_co_u32_e64 v73, s[0:1], -1, v85, s[0:1]
	v_add_co_u32_e64 v76, s[0:1], s30, v84
	s_nop 1
	v_addc_co_u32_e64 v77, s[0:1], -1, v85, s[0:1]
	v_add_co_u32_e64 v80, s[0:1], s31, v84
	s_nop 1
	v_addc_co_u32_e64 v81, s[0:1], -1, v85, s[0:1]
	s_nop 0
	global_load_dwordx4 v[56:59], v[56:57], off nt
	s_nop 0
	global_load_dwordx4 v[60:63], v[60:61], off nt
	s_nop 0
	global_load_dwordx4 v[64:67], v[64:65], off nt
	s_nop 0
	global_load_dwordx4 v[68:71], v[68:69], off nt
	s_nop 0
	global_load_dwordx4 v[72:75], v[72:73], off nt
	s_nop 0
	global_load_dwordx4 v[76:79], v[76:77], off nt
	s_nop 0
	global_load_dwordx4 v[80:83], v[80:81], off nt
	s_nop 0
	global_load_dwordx4 v[84:87], v[84:85], off nt
	v_lshl_add_u64 v[30:31], v[30:31], 0, s[16:17]
	s_mov_b32 s99, 11
.Lp0_pipe:
	v_lshl_add_u64 v[144:145], v[30:31], 0, v[28:29]
	v_add_co_u32_e64 v116, s[0:1], s15, v144
	s_nop 1
	v_addc_co_u32_e64 v117, s[0:1], -1, v145, s[0:1]
	v_add_co_u32_e64 v120, s[0:1], s24, v144
	s_nop 1
	v_addc_co_u32_e64 v121, s[0:1], -1, v145, s[0:1]
	v_add_co_u32_e64 v124, s[0:1], s25, v144
	s_nop 1
	v_addc_co_u32_e64 v125, s[0:1], -1, v145, s[0:1]
	v_add_co_u32_e64 v128, s[0:1], s26, v144
	s_nop 1
	v_addc_co_u32_e64 v129, s[0:1], -1, v145, s[0:1]
	v_add_co_u32_e64 v132, s[0:1], s27, v144
	s_nop 1
	v_addc_co_u32_e64 v133, s[0:1], -1, v145, s[0:1]
	v_add_co_u32_e64 v136, s[0:1], s30, v144
	s_nop 1
	v_addc_co_u32_e64 v137, s[0:1], -1, v145, s[0:1]
	v_add_co_u32_e64 v140, s[0:1], s31, v144
	s_nop 1
	v_addc_co_u32_e64 v141, s[0:1], -1, v145, s[0:1]
	s_nop 0
	global_load_dwordx4 v[116:119], v[116:117], off nt
	s_nop 0
	global_load_dwordx4 v[120:123], v[120:121], off nt
	s_nop 0
	global_load_dwordx4 v[124:127], v[124:125], off nt
	s_nop 0
	global_load_dwordx4 v[128:131], v[128:129], off nt
	s_nop 0
	global_load_dwordx4 v[132:135], v[132:133], off nt
	s_nop 0
	global_load_dwordx4 v[136:139], v[136:137], off nt
	s_nop 0
	global_load_dwordx4 v[140:143], v[140:141], off nt
	s_nop 0
	global_load_dwordx4 v[144:147], v[144:145], off nt
	v_lshl_add_u64 v[30:31], v[30:31], 0, s[16:17]
	ds_read_b128 v[20:23], v39
	ds_read_b128 v[40:43], v39 offset:336
	ds_read_b128 v[44:47], v39 offset:672
	ds_read_b128 v[48:51], v39 offset:1008
	ds_read_b128 v[52:55], v39 offset:1344
	ds_read_b128 v[88:91], v39 offset:1680
	ds_read_b128 v[92:95], v39 offset:2016
	ds_read_b128 v[96:99], v39 offset:2352
	v_add_u32_e32 v39, 0xa80, v39
	s_waitcnt lgkmcnt(0)
	v_mov_b32_e32 v100, v23
	v_mov_b32_e32 v102, v43
	v_mov_b32_e32 v104, v47
	v_mov_b32_e32 v106, v51
	v_mov_b32_e32 v108, v55
	v_mov_b32_e32 v110, v91
	v_mov_b32_e32 v112, v95
	v_mov_b32_e32 v114, v99
	s_waitcnt vmcnt(15)
	v_pk_fma_f32 v[18:19], v[58:59], v[20:21], v[18:19] op_sel_hi:[1,0,1]
	v_pk_fma_f32 v[16:17], v[56:57], v[20:21], v[16:17] op_sel_hi:[1,0,1]
	v_pk_fma_f32 v[14:15], v[58:59], v[20:21], v[14:15] op_sel:[0,1,0]
	v_pk_fma_f32 v[12:13], v[56:57], v[20:21], v[12:13] op_sel:[0,1,0]
	v_pk_fma_f32 v[10:11], v[58:59], v[22:23], v[10:11] op_sel_hi:[1,0,1]
	v_pk_fma_f32 v[8:9], v[56:57], v[22:23], v[8:9] op_sel_hi:[1,0,1]
	v_pk_fma_f32 v[6:7], v[58:59], v[100:101], v[6:7] op_sel_hi:[1,0,1]
	v_pk_fma_f32 v[4:5], v[56:57], v[100:101], v[4:5] op_sel_hi:[1,0,1]
	s_waitcnt vmcnt(14)
	v_pk_fma_f32 v[18:19], v[62:63], v[40:41], v[18:19] op_sel_hi:[1,0,1]
	v_pk_fma_f32 v[16:17], v[60:61], v[40:41], v[16:17] op_sel_hi:[1,0,1]
	v_pk_fma_f32 v[14:15], v[62:63], v[40:41], v[14:15] op_sel:[0,1,0]
	v_pk_fma_f32 v[12:13], v[60:61], v[40:41], v[12:13] op_sel:[0,1,0]
	v_pk_fma_f32 v[10:11], v[62:63], v[42:43], v[10:11] op_sel_hi:[1,0,1]
	v_pk_fma_f32 v[8:9], v[60:61], v[42:43], v[8:9] op_sel_hi:[1,0,1]
	v_pk_fma_f32 v[6:7], v[62:63], v[102:103], v[6:7] op_sel_hi:[1,0,1]
	v_pk_fma_f32 v[4:5], v[60:61], v[102:103], v[4:5] op_sel_hi:[1,0,1]
	s_waitcnt vmcnt(13)
	v_pk_fma_f32 v[18:19], v[66:67], v[44:45], v[18:19] op_sel_hi:[1,0,1]
	v_pk_fma_f32 v[16:17], v[64:65], v[44:45], v[16:17] op_sel_hi:[1,0,1]
	v_pk_fma_f32 v[14:15], v[66:67], v[44:45], v[14:15] op_sel:[0,1,0]
	v_pk_fma_f32 v[12:13], v[64:65], v[44:45], v[12:13] op_sel:[0,1,0]
	v_pk_fma_f32 v[10:11], v[66:67], v[46:47], v[10:11] op_sel_hi:[1,0,1]
	v_pk_fma_f32 v[8:9], v[64:65], v[46:47], v[8:9] op_sel_hi:[1,0,1]
	v_pk_fma_f32 v[6:7], v[66:67], v[104:105], v[6:7] op_sel_hi:[1,0,1]
	v_pk_fma_f32 v[4:5], v[64:65], v[104:105], v[4:5] op_sel_hi:[1,0,1]
	s_waitcnt vmcnt(12)
	v_pk_fma_f32 v[18:19], v[70:71], v[48:49], v[18:19] op_sel_hi:[1,0,1]
	v_pk_fma_f32 v[16:17], v[68:69], v[48:49], v[16:17] op_sel_hi:[1,0,1]
	v_pk_fma_f32 v[14:15], v[70:71], v[48:49], v[14:15] op_sel:[0,1,0]
	v_pk_fma_f32 v[12:13], v[68:69], v[48:49], v[12:13] op_sel:[0,1,0]
	v_pk_fma_f32 v[10:11], v[70:71], v[50:51], v[10:11] op_sel_hi:[1,0,1]
	v_pk_fma_f32 v[8:9], v[68:69], v[50:51], v[8:9] op_sel_hi:[1,0,1]
	v_pk_fma_f32 v[6:7], v[70:71], v[106:107], v[6:7] op_sel_hi:[1,0,1]
	v_pk_fma_f32 v[4:5], v[68:69], v[106:107], v[4:5] op_sel_hi:[1,0,1]
	s_waitcnt vmcnt(11)
	v_pk_fma_f32 v[18:19], v[74:75], v[52:53], v[18:19] op_sel_hi:[1,0,1]
	v_pk_fma_f32 v[16:17], v[72:73], v[52:53], v[16:17] op_sel_hi:[1,0,1]
	v_pk_fma_f32 v[14:15], v[74:75], v[52:53], v[14:15] op_sel:[0,1,0]
	v_pk_fma_f32 v[12:13], v[72:73], v[52:53], v[12:13] op_sel:[0,1,0]
	v_pk_fma_f32 v[10:11], v[74:75], v[54:55], v[10:11] op_sel_hi:[1,0,1]
	v_pk_fma_f32 v[8:9], v[72:73], v[54:55], v[8:9] op_sel_hi:[1,0,1]
	v_pk_fma_f32 v[6:7], v[74:75], v[108:109], v[6:7] op_sel_hi:[1,0,1]
	v_pk_fma_f32 v[4:5], v[72:73], v[108:109], v[4:5] op_sel_hi:[1,0,1]
	s_waitcnt vmcnt(10)
	v_pk_fma_f32 v[18:19], v[78:79], v[88:89], v[18:19] op_sel_hi:[1,0,1]
	v_pk_fma_f32 v[16:17], v[76:77], v[88:89], v[16:17] op_sel_hi:[1,0,1]
	v_pk_fma_f32 v[14:15], v[78:79], v[88:89], v[14:15] op_sel:[0,1,0]
	v_pk_fma_f32 v[12:13], v[76:77], v[88:89], v[12:13] op_sel:[0,1,0]
	v_pk_fma_f32 v[10:11], v[78:79], v[90:91], v[10:11] op_sel_hi:[1,0,1]
	v_pk_fma_f32 v[8:9], v[76:77], v[90:91], v[8:9] op_sel_hi:[1,0,1]
	v_pk_fma_f32 v[6:7], v[78:79], v[110:111], v[6:7] op_sel_hi:[1,0,1]
	v_pk_fma_f32 v[4:5], v[76:77], v[110:111], v[4:5] op_sel_hi:[1,0,1]
	s_waitcnt vmcnt(9)
	v_pk_fma_f32 v[18:19], v[82:83], v[92:93], v[18:19] op_sel_hi:[1,0,1]
	v_pk_fma_f32 v[16:17], v[80:81], v[92:93], v[16:17] op_sel_hi:[1,0,1]
	v_pk_fma_f32 v[14:15], v[82:83], v[92:93], v[14:15] op_sel:[0,1,0]
	v_pk_fma_f32 v[12:13], v[80:81], v[92:93], v[12:13] op_sel:[0,1,0]
	v_pk_fma_f32 v[10:11], v[82:83], v[94:95], v[10:11] op_sel_hi:[1,0,1]
	v_pk_fma_f32 v[8:9], v[80:81], v[94:95], v[8:9] op_sel_hi:[1,0,1]
	v_pk_fma_f32 v[6:7], v[82:83], v[112:113], v[6:7] op_sel_hi:[1,0,1]
	v_pk_fma_f32 v[4:5], v[80:81], v[112:113], v[4:5] op_sel_hi:[1,0,1]
	s_waitcnt vmcnt(8)
	v_pk_fma_f32 v[18:19], v[86:87], v[96:97], v[18:19] op_sel_hi:[1,0,1]
	v_pk_fma_f32 v[16:17], v[84:85], v[96:97], v[16:17] op_sel_hi:[1,0,1]
	v_pk_fma_f32 v[14:15], v[86:87], v[96:97], v[14:15] op_sel:[0,1,0]
	v_pk_fma_f32 v[12:13], v[84:85], v[96:97], v[12:13] op_sel:[0,1,0]
	v_pk_fma_f32 v[10:11], v[86:87], v[98:99], v[10:11] op_sel_hi:[1,0,1]
	v_pk_fma_f32 v[8:9], v[84:85], v[98:99], v[8:9] op_sel_hi:[1,0,1]
	v_pk_fma_f32 v[6:7], v[86:87], v[114:115], v[6:7] op_sel_hi:[1,0,1]
	v_pk_fma_f32 v[4:5], v[84:85], v[114:115], v[4:5] op_sel_hi:[1,0,1]
	v_lshl_add_u64 v[84:85], v[30:31], 0, v[28:29]
	v_add_co_u32_e64 v56, s[0:1], s15, v84
	s_nop 1
	v_addc_co_u32_e64 v57, s[0:1], -1, v85, s[0:1]
	v_add_co_u32_e64 v60, s[0:1], s24, v84
	s_nop 1
	v_addc_co_u32_e64 v61, s[0:1], -1, v85, s[0:1]
	v_add_co_u32_e64 v64, s[0:1], s25, v84
	s_nop 1
	v_addc_co_u32_e64 v65, s[0:1], -1, v85, s[0:1]
	v_add_co_u32_e64 v68, s[0:1], s26, v84
	s_nop 1
	v_addc_co_u32_e64 v69, s[0:1], -1, v85, s[0:1]
	v_add_co_u32_e64 v72, s[0:1], s27, v84
	s_nop 1
	v_addc_co_u32_e64 v73, s[0:1], -1, v85, s[0:1]
	v_add_co_u32_e64 v76, s[0:1], s30, v84
	s_nop 1
	v_addc_co_u32_e64 v77, s[0:1], -1, v85, s[0:1]
	v_add_co_u32_e64 v80, s[0:1], s31, v84
	s_nop 1
	v_addc_co_u32_e64 v81, s[0:1], -1, v85, s[0:1]
	s_nop 0
	global_load_dwordx4 v[56:59], v[56:57], off nt
	s_nop 0
	global_load_dwordx4 v[60:63], v[60:61], off nt
	s_nop 0
	global_load_dwordx4 v[64:67], v[64:65], off nt
	s_nop 0
	global_load_dwordx4 v[68:71], v[68:69], off nt
	s_nop 0
	global_load_dwordx4 v[72:75], v[72:73], off nt
	s_nop 0
	global_load_dwordx4 v[76:79], v[76:77], off nt
	s_nop 0
	global_load_dwordx4 v[80:83], v[80:81], off nt
	s_nop 0
	global_load_dwordx4 v[84:87], v[84:85], off nt
	v_lshl_add_u64 v[30:31], v[30:31], 0, s[16:17]
	ds_read_b128 v[20:23], v39
	ds_read_b128 v[40:43], v39 offset:336
	ds_read_b128 v[44:47], v39 offset:672
	ds_read_b128 v[48:51], v39 offset:1008
	ds_read_b128 v[52:55], v39 offset:1344
	ds_read_b128 v[88:91], v39 offset:1680
	ds_read_b128 v[92:95], v39 offset:2016
	ds_read_b128 v[96:99], v39 offset:2352
	v_add_u32_e32 v39, 0xa80, v39
	s_waitcnt lgkmcnt(0)
	v_mov_b32_e32 v100, v23
	v_mov_b32_e32 v102, v43
	v_mov_b32_e32 v104, v47
	v_mov_b32_e32 v106, v51
	v_mov_b32_e32 v108, v55
	v_mov_b32_e32 v110, v91
	v_mov_b32_e32 v112, v95
	v_mov_b32_e32 v114, v99
	s_waitcnt vmcnt(15)
	v_pk_fma_f32 v[18:19], v[118:119], v[20:21], v[18:19] op_sel_hi:[1,0,1]
	v_pk_fma_f32 v[16:17], v[116:117], v[20:21], v[16:17] op_sel_hi:[1,0,1]
	v_pk_fma_f32 v[14:15], v[118:119], v[20:21], v[14:15] op_sel:[0,1,0]
	v_pk_fma_f32 v[12:13], v[116:117], v[20:21], v[12:13] op_sel:[0,1,0]
	v_pk_fma_f32 v[10:11], v[118:119], v[22:23], v[10:11] op_sel_hi:[1,0,1]
	v_pk_fma_f32 v[8:9], v[116:117], v[22:23], v[8:9] op_sel_hi:[1,0,1]
	v_pk_fma_f32 v[6:7], v[118:119], v[100:101], v[6:7] op_sel_hi:[1,0,1]
	v_pk_fma_f32 v[4:5], v[116:117], v[100:101], v[4:5] op_sel_hi:[1,0,1]
	s_waitcnt vmcnt(14)
	v_pk_fma_f32 v[18:19], v[122:123], v[40:41], v[18:19] op_sel_hi:[1,0,1]
	v_pk_fma_f32 v[16:17], v[120:121], v[40:41], v[16:17] op_sel_hi:[1,0,1]
	v_pk_fma_f32 v[14:15], v[122:123], v[40:41], v[14:15] op_sel:[0,1,0]
	v_pk_fma_f32 v[12:13], v[120:121], v[40:41], v[12:13] op_sel:[0,1,0]
	v_pk_fma_f32 v[10:11], v[122:123], v[42:43], v[10:11] op_sel_hi:[1,0,1]
	v_pk_fma_f32 v[8:9], v[120:121], v[42:43], v[8:9] op_sel_hi:[1,0,1]
	v_pk_fma_f32 v[6:7], v[122:123], v[102:103], v[6:7] op_sel_hi:[1,0,1]
	v_pk_fma_f32 v[4:5], v[120:121], v[102:103], v[4:5] op_sel_hi:[1,0,1]
	s_waitcnt vmcnt(13)
	v_pk_fma_f32 v[18:19], v[126:127], v[44:45], v[18:19] op_sel_hi:[1,0,1]
	v_pk_fma_f32 v[16:17], v[124:125], v[44:45], v[16:17] op_sel_hi:[1,0,1]
	v_pk_fma_f32 v[14:15], v[126:127], v[44:45], v[14:15] op_sel:[0,1,0]
	v_pk_fma_f32 v[12:13], v[124:125], v[44:45], v[12:13] op_sel:[0,1,0]
	v_pk_fma_f32 v[10:11], v[126:127], v[46:47], v[10:11] op_sel_hi:[1,0,1]
	v_pk_fma_f32 v[8:9], v[124:125], v[46:47], v[8:9] op_sel_hi:[1,0,1]
	v_pk_fma_f32 v[6:7], v[126:127], v[104:105], v[6:7] op_sel_hi:[1,0,1]
	v_pk_fma_f32 v[4:5], v[124:125], v[104:105], v[4:5] op_sel_hi:[1,0,1]
	s_waitcnt vmcnt(12)
	v_pk_fma_f32 v[18:19], v[130:131], v[48:49], v[18:19] op_sel_hi:[1,0,1]
	v_pk_fma_f32 v[16:17], v[128:129], v[48:49], v[16:17] op_sel_hi:[1,0,1]
	v_pk_fma_f32 v[14:15], v[130:131], v[48:49], v[14:15] op_sel:[0,1,0]
	v_pk_fma_f32 v[12:13], v[128:129], v[48:49], v[12:13] op_sel:[0,1,0]
	v_pk_fma_f32 v[10:11], v[130:131], v[50:51], v[10:11] op_sel_hi:[1,0,1]
	v_pk_fma_f32 v[8:9], v[128:129], v[50:51], v[8:9] op_sel_hi:[1,0,1]
	v_pk_fma_f32 v[6:7], v[130:131], v[106:107], v[6:7] op_sel_hi:[1,0,1]
	v_pk_fma_f32 v[4:5], v[128:129], v[106:107], v[4:5] op_sel_hi:[1,0,1]
	s_waitcnt vmcnt(11)
	v_pk_fma_f32 v[18:19], v[134:135], v[52:53], v[18:19] op_sel_hi:[1,0,1]
	v_pk_fma_f32 v[16:17], v[132:133], v[52:53], v[16:17] op_sel_hi:[1,0,1]
	v_pk_fma_f32 v[14:15], v[134:135], v[52:53], v[14:15] op_sel:[0,1,0]
	v_pk_fma_f32 v[12:13], v[132:133], v[52:53], v[12:13] op_sel:[0,1,0]
	v_pk_fma_f32 v[10:11], v[134:135], v[54:55], v[10:11] op_sel_hi:[1,0,1]
	v_pk_fma_f32 v[8:9], v[132:133], v[54:55], v[8:9] op_sel_hi:[1,0,1]
	v_pk_fma_f32 v[6:7], v[134:135], v[108:109], v[6:7] op_sel_hi:[1,0,1]
	v_pk_fma_f32 v[4:5], v[132:133], v[108:109], v[4:5] op_sel_hi:[1,0,1]
	s_waitcnt vmcnt(10)
	v_pk_fma_f32 v[18:19], v[138:139], v[88:89], v[18:19] op_sel_hi:[1,0,1]
	v_pk_fma_f32 v[16:17], v[136:137], v[88:89], v[16:17] op_sel_hi:[1,0,1]
	v_pk_fma_f32 v[14:15], v[138:139], v[88:89], v[14:15] op_sel:[0,1,0]
	v_pk_fma_f32 v[12:13], v[136:137], v[88:89], v[12:13] op_sel:[0,1,0]
	v_pk_fma_f32 v[10:11], v[138:139], v[90:91], v[10:11] op_sel_hi:[1,0,1]
	v_pk_fma_f32 v[8:9], v[136:137], v[90:91], v[8:9] op_sel_hi:[1,0,1]
	v_pk_fma_f32 v[6:7], v[138:139], v[110:111], v[6:7] op_sel_hi:[1,0,1]
	v_pk_fma_f32 v[4:5], v[136:137], v[110:111], v[4:5] op_sel_hi:[1,0,1]
	s_waitcnt vmcnt(9)
	v_pk_fma_f32 v[18:19], v[142:143], v[92:93], v[18:19] op_sel_hi:[1,0,1]
	v_pk_fma_f32 v[16:17], v[140:141], v[92:93], v[16:17] op_sel_hi:[1,0,1]
	v_pk_fma_f32 v[14:15], v[142:143], v[92:93], v[14:15] op_sel:[0,1,0]
	v_pk_fma_f32 v[12:13], v[140:141], v[92:93], v[12:13] op_sel:[0,1,0]
	v_pk_fma_f32 v[10:11], v[142:143], v[94:95], v[10:11] op_sel_hi:[1,0,1]
	v_pk_fma_f32 v[8:9], v[140:141], v[94:95], v[8:9] op_sel_hi:[1,0,1]
	v_pk_fma_f32 v[6:7], v[142:143], v[112:113], v[6:7] op_sel_hi:[1,0,1]
	v_pk_fma_f32 v[4:5], v[140:141], v[112:113], v[4:5] op_sel_hi:[1,0,1]
	s_waitcnt vmcnt(8)
	v_pk_fma_f32 v[18:19], v[146:147], v[96:97], v[18:19] op_sel_hi:[1,0,1]
	v_pk_fma_f32 v[16:17], v[144:145], v[96:97], v[16:17] op_sel_hi:[1,0,1]
	v_pk_fma_f32 v[14:15], v[146:147], v[96:97], v[14:15] op_sel:[0,1,0]
	v_pk_fma_f32 v[12:13], v[144:145], v[96:97], v[12:13] op_sel:[0,1,0]
	v_pk_fma_f32 v[10:11], v[146:147], v[98:99], v[10:11] op_sel_hi:[1,0,1]
	v_pk_fma_f32 v[8:9], v[144:145], v[98:99], v[8:9] op_sel_hi:[1,0,1]
	v_pk_fma_f32 v[6:7], v[146:147], v[114:115], v[6:7] op_sel_hi:[1,0,1]
	v_pk_fma_f32 v[4:5], v[144:145], v[114:115], v[4:5] op_sel_hi:[1,0,1]
	s_sub_u32 s99, s99, 1
	s_cmp_lg_u32 s99, 0
	s_cbranch_scc1 .Lp0_pipe
	v_lshl_add_u64 v[144:145], v[30:31], 0, v[28:29]
	v_add_co_u32_e64 v116, s[0:1], s15, v144
	s_nop 1
	v_addc_co_u32_e64 v117, s[0:1], -1, v145, s[0:1]
	v_add_co_u32_e64 v120, s[0:1], s24, v144
	s_nop 1
	v_addc_co_u32_e64 v121, s[0:1], -1, v145, s[0:1]
	v_add_co_u32_e64 v124, s[0:1], s25, v144
	s_nop 1
	v_addc_co_u32_e64 v125, s[0:1], -1, v145, s[0:1]
	v_add_co_u32_e64 v128, s[0:1], s26, v144
	s_nop 1
	v_addc_co_u32_e64 v129, s[0:1], -1, v145, s[0:1]
	v_add_co_u32_e64 v132, s[0:1], s27, v144
	s_nop 1
	v_addc_co_u32_e64 v133, s[0:1], -1, v145, s[0:1]
	v_add_co_u32_e64 v136, s[0:1], s30, v144
	s_nop 1
	v_addc_co_u32_e64 v137, s[0:1], -1, v145, s[0:1]
	v_add_co_u32_e64 v140, s[0:1], s31, v144
	s_nop 1
	v_addc_co_u32_e64 v141, s[0:1], -1, v145, s[0:1]
	s_nop 0
	global_load_dwordx4 v[116:119], v[116:117], off nt
	s_nop 0
	global_load_dwordx4 v[120:123], v[120:121], off nt
	s_nop 0
	global_load_dwordx4 v[124:127], v[124:125], off nt
	s_nop 0
	global_load_dwordx4 v[128:131], v[128:129], off nt
	s_nop 0
	global_load_dwordx4 v[132:135], v[132:133], off nt
	s_nop 0
	global_load_dwordx4 v[136:139], v[136:137], off nt
	s_nop 0
	global_load_dwordx4 v[140:143], v[140:141], off nt
	s_nop 0
	global_load_dwordx4 v[144:147], v[144:145], off nt
	v_lshl_add_u64 v[30:31], v[30:31], 0, s[16:17]
	ds_read_b128 v[20:23], v39
	ds_read_b128 v[40:43], v39 offset:336
	ds_read_b128 v[44:47], v39 offset:672
	ds_read_b128 v[48:51], v39 offset:1008
	ds_read_b128 v[52:55], v39 offset:1344
	ds_read_b128 v[88:91], v39 offset:1680
	ds_read_b128 v[92:95], v39 offset:2016
	ds_read_b128 v[96:99], v39 offset:2352
	v_add_u32_e32 v39, 0xa80, v39
	s_waitcnt lgkmcnt(0)
	v_mov_b32_e32 v100, v23
	v_mov_b32_e32 v102, v43
	v_mov_b32_e32 v104, v47
	v_mov_b32_e32 v106, v51
	v_mov_b32_e32 v108, v55
	v_mov_b32_e32 v110, v91
	v_mov_b32_e32 v112, v95
	v_mov_b32_e32 v114, v99
	s_waitcnt vmcnt(15)
	v_pk_fma_f32 v[18:19], v[58:59], v[20:21], v[18:19] op_sel_hi:[1,0,1]
	v_pk_fma_f32 v[16:17], v[56:57], v[20:21], v[16:17] op_sel_hi:[1,0,1]
	v_pk_fma_f32 v[14:15], v[58:59], v[20:21], v[14:15] op_sel:[0,1,0]
	v_pk_fma_f32 v[12:13], v[56:57], v[20:21], v[12:13] op_sel:[0,1,0]
	v_pk_fma_f32 v[10:11], v[58:59], v[22:23], v[10:11] op_sel_hi:[1,0,1]
	v_pk_fma_f32 v[8:9], v[56:57], v[22:23], v[8:9] op_sel_hi:[1,0,1]
	v_pk_fma_f32 v[6:7], v[58:59], v[100:101], v[6:7] op_sel_hi:[1,0,1]
	v_pk_fma_f32 v[4:5], v[56:57], v[100:101], v[4:5] op_sel_hi:[1,0,1]
	s_waitcnt vmcnt(14)
	v_pk_fma_f32 v[18:19], v[62:63], v[40:41], v[18:19] op_sel_hi:[1,0,1]
	v_pk_fma_f32 v[16:17], v[60:61], v[40:41], v[16:17] op_sel_hi:[1,0,1]
	v_pk_fma_f32 v[14:15], v[62:63], v[40:41], v[14:15] op_sel:[0,1,0]
	v_pk_fma_f32 v[12:13], v[60:61], v[40:41], v[12:13] op_sel:[0,1,0]
	v_pk_fma_f32 v[10:11], v[62:63], v[42:43], v[10:11] op_sel_hi:[1,0,1]
	v_pk_fma_f32 v[8:9], v[60:61], v[42:43], v[8:9] op_sel_hi:[1,0,1]
	v_pk_fma_f32 v[6:7], v[62:63], v[102:103], v[6:7] op_sel_hi:[1,0,1]
	v_pk_fma_f32 v[4:5], v[60:61], v[102:103], v[4:5] op_sel_hi:[1,0,1]
	s_waitcnt vmcnt(13)
	v_pk_fma_f32 v[18:19], v[66:67], v[44:45], v[18:19] op_sel_hi:[1,0,1]
	v_pk_fma_f32 v[16:17], v[64:65], v[44:45], v[16:17] op_sel_hi:[1,0,1]
	v_pk_fma_f32 v[14:15], v[66:67], v[44:45], v[14:15] op_sel:[0,1,0]
	v_pk_fma_f32 v[12:13], v[64:65], v[44:45], v[12:13] op_sel:[0,1,0]
	v_pk_fma_f32 v[10:11], v[66:67], v[46:47], v[10:11] op_sel_hi:[1,0,1]
	v_pk_fma_f32 v[8:9], v[64:65], v[46:47], v[8:9] op_sel_hi:[1,0,1]
	v_pk_fma_f32 v[6:7], v[66:67], v[104:105], v[6:7] op_sel_hi:[1,0,1]
	v_pk_fma_f32 v[4:5], v[64:65], v[104:105], v[4:5] op_sel_hi:[1,0,1]
	s_waitcnt vmcnt(12)
	v_pk_fma_f32 v[18:19], v[70:71], v[48:49], v[18:19] op_sel_hi:[1,0,1]
	v_pk_fma_f32 v[16:17], v[68:69], v[48:49], v[16:17] op_sel_hi:[1,0,1]
	v_pk_fma_f32 v[14:15], v[70:71], v[48:49], v[14:15] op_sel:[0,1,0]
	v_pk_fma_f32 v[12:13], v[68:69], v[48:49], v[12:13] op_sel:[0,1,0]
	v_pk_fma_f32 v[10:11], v[70:71], v[50:51], v[10:11] op_sel_hi:[1,0,1]
	v_pk_fma_f32 v[8:9], v[68:69], v[50:51], v[8:9] op_sel_hi:[1,0,1]
	v_pk_fma_f32 v[6:7], v[70:71], v[106:107], v[6:7] op_sel_hi:[1,0,1]
	v_pk_fma_f32 v[4:5], v[68:69], v[106:107], v[4:5] op_sel_hi:[1,0,1]
	s_waitcnt vmcnt(11)
	v_pk_fma_f32 v[18:19], v[74:75], v[52:53], v[18:19] op_sel_hi:[1,0,1]
	v_pk_fma_f32 v[16:17], v[72:73], v[52:53], v[16:17] op_sel_hi:[1,0,1]
	v_pk_fma_f32 v[14:15], v[74:75], v[52:53], v[14:15] op_sel:[0,1,0]
	v_pk_fma_f32 v[12:13], v[72:73], v[52:53], v[12:13] op_sel:[0,1,0]
	v_pk_fma_f32 v[10:11], v[74:75], v[54:55], v[10:11] op_sel_hi:[1,0,1]
	v_pk_fma_f32 v[8:9], v[72:73], v[54:55], v[8:9] op_sel_hi:[1,0,1]
	v_pk_fma_f32 v[6:7], v[74:75], v[108:109], v[6:7] op_sel_hi:[1,0,1]
	v_pk_fma_f32 v[4:5], v[72:73], v[108:109], v[4:5] op_sel_hi:[1,0,1]
	s_waitcnt vmcnt(10)
	v_pk_fma_f32 v[18:19], v[78:79], v[88:89], v[18:19] op_sel_hi:[1,0,1]
	v_pk_fma_f32 v[16:17], v[76:77], v[88:89], v[16:17] op_sel_hi:[1,0,1]
	v_pk_fma_f32 v[14:15], v[78:79], v[88:89], v[14:15] op_sel:[0,1,0]
	v_pk_fma_f32 v[12:13], v[76:77], v[88:89], v[12:13] op_sel:[0,1,0]
	v_pk_fma_f32 v[10:11], v[78:79], v[90:91], v[10:11] op_sel_hi:[1,0,1]
	v_pk_fma_f32 v[8:9], v[76:77], v[90:91], v[8:9] op_sel_hi:[1,0,1]
	v_pk_fma_f32 v[6:7], v[78:79], v[110:111], v[6:7] op_sel_hi:[1,0,1]
	v_pk_fma_f32 v[4:5], v[76:77], v[110:111], v[4:5] op_sel_hi:[1,0,1]
	s_waitcnt vmcnt(9)
	v_pk_fma_f32 v[18:19], v[82:83], v[92:93], v[18:19] op_sel_hi:[1,0,1]
	v_pk_fma_f32 v[16:17], v[80:81], v[92:93], v[16:17] op_sel_hi:[1,0,1]
	v_pk_fma_f32 v[14:15], v[82:83], v[92:93], v[14:15] op_sel:[0,1,0]
	v_pk_fma_f32 v[12:13], v[80:81], v[92:93], v[12:13] op_sel:[0,1,0]
	v_pk_fma_f32 v[10:11], v[82:83], v[94:95], v[10:11] op_sel_hi:[1,0,1]
	v_pk_fma_f32 v[8:9], v[80:81], v[94:95], v[8:9] op_sel_hi:[1,0,1]
	v_pk_fma_f32 v[6:7], v[82:83], v[112:113], v[6:7] op_sel_hi:[1,0,1]
	v_pk_fma_f32 v[4:5], v[80:81], v[112:113], v[4:5] op_sel_hi:[1,0,1]
	s_waitcnt vmcnt(8)
	v_pk_fma_f32 v[18:19], v[86:87], v[96:97], v[18:19] op_sel_hi:[1,0,1]
	v_pk_fma_f32 v[16:17], v[84:85], v[96:97], v[16:17] op_sel_hi:[1,0,1]
	v_pk_fma_f32 v[14:15], v[86:87], v[96:97], v[14:15] op_sel:[0,1,0]
	v_pk_fma_f32 v[12:13], v[84:85], v[96:97], v[12:13] op_sel:[0,1,0]
	v_pk_fma_f32 v[10:11], v[86:87], v[98:99], v[10:11] op_sel_hi:[1,0,1]
	v_pk_fma_f32 v[8:9], v[84:85], v[98:99], v[8:9] op_sel_hi:[1,0,1]
	v_pk_fma_f32 v[6:7], v[86:87], v[114:115], v[6:7] op_sel_hi:[1,0,1]
	v_pk_fma_f32 v[4:5], v[84:85], v[114:115], v[4:5] op_sel_hi:[1,0,1]
	ds_read_b128 v[20:23], v39
	ds_read_b128 v[40:43], v39 offset:336
	ds_read_b128 v[44:47], v39 offset:672
	ds_read_b128 v[48:51], v39 offset:1008
	ds_read_b128 v[52:55], v39 offset:1344
	ds_read_b128 v[88:91], v39 offset:1680
	ds_read_b128 v[92:95], v39 offset:2016
	ds_read_b128 v[96:99], v39 offset:2352
	v_add_u32_e32 v39, 0xa80, v39
	s_waitcnt lgkmcnt(0)
	v_mov_b32_e32 v100, v23
	v_mov_b32_e32 v102, v43
	v_mov_b32_e32 v104, v47
	v_mov_b32_e32 v106, v51
	v_mov_b32_e32 v108, v55
	v_mov_b32_e32 v110, v91
	v_mov_b32_e32 v112, v95
	v_mov_b32_e32 v114, v99
	s_waitcnt vmcnt(7)
	v_pk_fma_f32 v[18:19], v[118:119], v[20:21], v[18:19] op_sel_hi:[1,0,1]
	v_pk_fma_f32 v[16:17], v[116:117], v[20:21], v[16:17] op_sel_hi:[1,0,1]
	v_pk_fma_f32 v[14:15], v[118:119], v[20:21], v[14:15] op_sel:[0,1,0]
	v_pk_fma_f32 v[12:13], v[116:117], v[20:21], v[12:13] op_sel:[0,1,0]
	v_pk_fma_f32 v[10:11], v[118:119], v[22:23], v[10:11] op_sel_hi:[1,0,1]
	v_pk_fma_f32 v[8:9], v[116:117], v[22:23], v[8:9] op_sel_hi:[1,0,1]
	v_pk_fma_f32 v[6:7], v[118:119], v[100:101], v[6:7] op_sel_hi:[1,0,1]
	v_pk_fma_f32 v[4:5], v[116:117], v[100:101], v[4:5] op_sel_hi:[1,0,1]
	s_waitcnt vmcnt(6)
	v_pk_fma_f32 v[18:19], v[122:123], v[40:41], v[18:19] op_sel_hi:[1,0,1]
	v_pk_fma_f32 v[16:17], v[120:121], v[40:41], v[16:17] op_sel_hi:[1,0,1]
	v_pk_fma_f32 v[14:15], v[122:123], v[40:41], v[14:15] op_sel:[0,1,0]
	v_pk_fma_f32 v[12:13], v[120:121], v[40:41], v[12:13] op_sel:[0,1,0]
	v_pk_fma_f32 v[10:11], v[122:123], v[42:43], v[10:11] op_sel_hi:[1,0,1]
	v_pk_fma_f32 v[8:9], v[120:121], v[42:43], v[8:9] op_sel_hi:[1,0,1]
	v_pk_fma_f32 v[6:7], v[122:123], v[102:103], v[6:7] op_sel_hi:[1,0,1]
	v_pk_fma_f32 v[4:5], v[120:121], v[102:103], v[4:5] op_sel_hi:[1,0,1]
	s_waitcnt vmcnt(5)
	v_pk_fma_f32 v[18:19], v[126:127], v[44:45], v[18:19] op_sel_hi:[1,0,1]
	v_pk_fma_f32 v[16:17], v[124:125], v[44:45], v[16:17] op_sel_hi:[1,0,1]
	v_pk_fma_f32 v[14:15], v[126:127], v[44:45], v[14:15] op_sel:[0,1,0]
	v_pk_fma_f32 v[12:13], v[124:125], v[44:45], v[12:13] op_sel:[0,1,0]
	v_pk_fma_f32 v[10:11], v[126:127], v[46:47], v[10:11] op_sel_hi:[1,0,1]
	v_pk_fma_f32 v[8:9], v[124:125], v[46:47], v[8:9] op_sel_hi:[1,0,1]
	v_pk_fma_f32 v[6:7], v[126:127], v[104:105], v[6:7] op_sel_hi:[1,0,1]
	v_pk_fma_f32 v[4:5], v[124:125], v[104:105], v[4:5] op_sel_hi:[1,0,1]
	s_waitcnt vmcnt(4)
	v_pk_fma_f32 v[18:19], v[130:131], v[48:49], v[18:19] op_sel_hi:[1,0,1]
	v_pk_fma_f32 v[16:17], v[128:129], v[48:49], v[16:17] op_sel_hi:[1,0,1]
	v_pk_fma_f32 v[14:15], v[130:131], v[48:49], v[14:15] op_sel:[0,1,0]
	v_pk_fma_f32 v[12:13], v[128:129], v[48:49], v[12:13] op_sel:[0,1,0]
	v_pk_fma_f32 v[10:11], v[130:131], v[50:51], v[10:11] op_sel_hi:[1,0,1]
	v_pk_fma_f32 v[8:9], v[128:129], v[50:51], v[8:9] op_sel_hi:[1,0,1]
	v_pk_fma_f32 v[6:7], v[130:131], v[106:107], v[6:7] op_sel_hi:[1,0,1]
	v_pk_fma_f32 v[4:5], v[128:129], v[106:107], v[4:5] op_sel_hi:[1,0,1]
	s_waitcnt vmcnt(3)
	v_pk_fma_f32 v[18:19], v[134:135], v[52:53], v[18:19] op_sel_hi:[1,0,1]
	v_pk_fma_f32 v[16:17], v[132:133], v[52:53], v[16:17] op_sel_hi:[1,0,1]
	v_pk_fma_f32 v[14:15], v[134:135], v[52:53], v[14:15] op_sel:[0,1,0]
	v_pk_fma_f32 v[12:13], v[132:133], v[52:53], v[12:13] op_sel:[0,1,0]
	v_pk_fma_f32 v[10:11], v[134:135], v[54:55], v[10:11] op_sel_hi:[1,0,1]
	v_pk_fma_f32 v[8:9], v[132:133], v[54:55], v[8:9] op_sel_hi:[1,0,1]
	v_pk_fma_f32 v[6:7], v[134:135], v[108:109], v[6:7] op_sel_hi:[1,0,1]
	v_pk_fma_f32 v[4:5], v[132:133], v[108:109], v[4:5] op_sel_hi:[1,0,1]
	s_waitcnt vmcnt(2)
	v_pk_fma_f32 v[18:19], v[138:139], v[88:89], v[18:19] op_sel_hi:[1,0,1]
	v_pk_fma_f32 v[16:17], v[136:137], v[88:89], v[16:17] op_sel_hi:[1,0,1]
	v_pk_fma_f32 v[14:15], v[138:139], v[88:89], v[14:15] op_sel:[0,1,0]
	v_pk_fma_f32 v[12:13], v[136:137], v[88:89], v[12:13] op_sel:[0,1,0]
	v_pk_fma_f32 v[10:11], v[138:139], v[90:91], v[10:11] op_sel_hi:[1,0,1]
	v_pk_fma_f32 v[8:9], v[136:137], v[90:91], v[8:9] op_sel_hi:[1,0,1]
	v_pk_fma_f32 v[6:7], v[138:139], v[110:111], v[6:7] op_sel_hi:[1,0,1]
	v_pk_fma_f32 v[4:5], v[136:137], v[110:111], v[4:5] op_sel_hi:[1,0,1]
	s_waitcnt vmcnt(1)
	v_pk_fma_f32 v[18:19], v[142:143], v[92:93], v[18:19] op_sel_hi:[1,0,1]
	v_pk_fma_f32 v[16:17], v[140:141], v[92:93], v[16:17] op_sel_hi:[1,0,1]
	v_pk_fma_f32 v[14:15], v[142:143], v[92:93], v[14:15] op_sel:[0,1,0]
	v_pk_fma_f32 v[12:13], v[140:141], v[92:93], v[12:13] op_sel:[0,1,0]
	v_pk_fma_f32 v[10:11], v[142:143], v[94:95], v[10:11] op_sel_hi:[1,0,1]
	v_pk_fma_f32 v[8:9], v[140:141], v[94:95], v[8:9] op_sel_hi:[1,0,1]
	v_pk_fma_f32 v[6:7], v[142:143], v[112:113], v[6:7] op_sel_hi:[1,0,1]
	v_pk_fma_f32 v[4:5], v[140:141], v[112:113], v[4:5] op_sel_hi:[1,0,1]
	s_waitcnt vmcnt(0)
	v_pk_fma_f32 v[18:19], v[146:147], v[96:97], v[18:19] op_sel_hi:[1,0,1]
	v_pk_fma_f32 v[16:17], v[144:145], v[96:97], v[16:17] op_sel_hi:[1,0,1]
	v_pk_fma_f32 v[14:15], v[146:147], v[96:97], v[14:15] op_sel:[0,1,0]
	v_pk_fma_f32 v[12:13], v[144:145], v[96:97], v[12:13] op_sel:[0,1,0]
	v_pk_fma_f32 v[10:11], v[146:147], v[98:99], v[10:11] op_sel_hi:[1,0,1]
	v_pk_fma_f32 v[8:9], v[144:145], v[98:99], v[8:9] op_sel_hi:[1,0,1]
	v_pk_fma_f32 v[6:7], v[146:147], v[114:115], v[6:7] op_sel_hi:[1,0,1]
	v_pk_fma_f32 v[4:5], v[144:145], v[114:115], v[4:5] op_sel_hi:[1,0,1]
	s_or_b64 exec, exec, s[20:21]
	ds_write_b128 v37, v[16:19]
	ds_write_b128 v37, v[12:15] offset:16
	ds_write_b128 v37, v[8:11] offset:32
	ds_write_b128 v37, v[4:7] offset:48

.LBB0_224:
	ds_read_b128 v[130:133], v208
	ds_read_b128 v[134:137], v208 offset:1024
	ds_read_b128 v[138:141], v208 offset:2048
	ds_read_b128 v[142:145], v208 offset:3072
	ds_read_b128 v[146:149], v209
	ds_read_b128 v[150:153], v209 offset:1024
	ds_read_b128 v[154:157], v209 offset:2048
	ds_read_b128 v[158:161], v209 offset:3072
	s_add_u32 s52, s50, 0xfff00080
	s_addc_u32 s53, s51, -1
	s_cmp_eq_u32 s89, 60
	s_cselect_b32 s55, s43, s53
	s_cselect_b32 s54, s85, s52
	s_cselect_b32 s53, s41, s88
	s_cselect_b32 s52, s86, s87
	v_lshl_add_u64 v[204:205], s[50:51], 0, v[192:193]
	s_add_i32 m0, s56, 0xc000
	ds_read_b128 v[162:165], v210
	ds_read_b128 v[166:169], v210 offset:1024
	ds_read_b128 v[170:173], v210 offset:2048
	ds_read_b128 v[174:177], v210 offset:3072
	ds_read_b128 v[200:203], v210 offset:4096
	ds_read_b128 v[212:215], v210 offset:5120
	ds_read_b128 v[216:219], v210 offset:6144
	ds_read_b128 v[224:227], v210 offset:7168
	global_load_lds_dwordx4 v[204:205], off
	v_lshl_add_u64 v[204:205], s[50:51], 0, v[194:195]
	s_add_i32 m0, s56, 0xe000
	s_nop 0
	global_load_lds_dwordx4 v[204:205], off
	s_waitcnt vmcnt(8)
	s_waitcnt lgkmcnt(0)
	s_setprio 1
	s_barrier
	v_mfma_f32_16x16x32_bf16 v[126:129], v[130:133], v[162:165], v[126:129]
	v_mfma_f32_16x16x32_bf16 v[122:125], v[138:141], v[162:165], v[122:125]
	v_mfma_f32_16x16x32_bf16 v[110:113], v[130:133], v[170:173], v[110:113]
	v_mfma_f32_16x16x32_bf16 v[106:109], v[138:141], v[170:173], v[106:109]
	v_mfma_f32_16x16x32_bf16 v[94:97], v[130:133], v[200:203], v[94:97]
	v_mfma_f32_16x16x32_bf16 v[90:93], v[138:141], v[200:203], v[90:93]
	v_mfma_f32_16x16x32_bf16 v[78:81], v[130:133], v[216:219], v[78:81]
	v_mfma_f32_16x16x32_bf16 v[74:77], v[138:141], v[216:219], v[74:77]
	v_mfma_f32_16x16x32_bf16 v[126:129], v[134:137], v[166:169], v[126:129]
	v_mfma_f32_16x16x32_bf16 v[122:125], v[142:145], v[166:169], v[122:125]
	v_mfma_f32_16x16x32_bf16 v[110:113], v[134:137], v[174:177], v[110:113]
	v_mfma_f32_16x16x32_bf16 v[106:109], v[142:145], v[174:177], v[106:109]
	v_mfma_f32_16x16x32_bf16 v[94:97], v[134:137], v[212:215], v[94:97]
	v_mfma_f32_16x16x32_bf16 v[90:93], v[142:145], v[212:215], v[90:93]
	v_mfma_f32_16x16x32_bf16 v[78:81], v[134:137], v[224:227], v[78:81]
	v_mfma_f32_16x16x32_bf16 v[74:77], v[142:145], v[224:227], v[74:77]
	s_setprio 0
	s_setprio 1
	v_mfma_f32_16x16x32_bf16 v[118:121], v[146:149], v[162:165], v[118:121]
	v_mfma_f32_16x16x32_bf16 v[114:117], v[154:157], v[162:165], v[114:117]
	v_mfma_f32_16x16x32_bf16 v[102:105], v[146:149], v[170:173], v[102:105]
	v_mfma_f32_16x16x32_bf16 v[98:101], v[154:157], v[170:173], v[98:101]
	v_mfma_f32_16x16x32_bf16 v[86:89], v[146:149], v[200:203], v[86:89]
	v_mfma_f32_16x16x32_bf16 v[82:85], v[154:157], v[200:203], v[82:85]
	v_mfma_f32_16x16x32_bf16 v[70:73], v[146:149], v[216:219], v[70:73]
	v_mfma_f32_16x16x32_bf16 v[66:69], v[154:157], v[216:219], v[66:69]
	v_mfma_f32_16x16x32_bf16 v[118:121], v[150:153], v[166:169], v[118:121]
	v_mfma_f32_16x16x32_bf16 v[114:117], v[158:161], v[166:169], v[114:117]
	v_mfma_f32_16x16x32_bf16 v[102:105], v[150:153], v[174:177], v[102:105]
	v_mfma_f32_16x16x32_bf16 v[98:101], v[158:161], v[174:177], v[98:101]
	v_mfma_f32_16x16x32_bf16 v[86:89], v[150:153], v[212:215], v[86:89]
	v_mfma_f32_16x16x32_bf16 v[82:85], v[158:161], v[212:215], v[82:85]
	v_mfma_f32_16x16x32_bf16 v[70:73], v[150:153], v[224:227], v[70:73]
	v_mfma_f32_16x16x32_bf16 v[66:69], v[158:161], v[224:227], v[66:69]
	s_barrier
	s_setprio 0
	s_add_i32 s90, s65, s31
	v_lshl_add_u64 v[204:205], s[52:53], 0, v[182:183]
	s_mov_b32 m0, s90
	ds_read_b128 v[162:165], v210 offset:16384
	ds_read_b128 v[166:169], v210 offset:17408
	ds_read_b128 v[170:173], v210 offset:18432
	ds_read_b128 v[174:177], v210 offset:19456
	ds_read_b128 v[200:203], v210 offset:20480
	ds_read_b128 v[212:215], v210 offset:21504
	ds_read_b128 v[216:219], v210 offset:22528
	ds_read_b128 v[224:227], v210 offset:23552
	global_load_lds_dwordx4 v[204:205], off
	s_add_i32 m0, s90, 0x2000
	s_add_u32 s90, s52, 0x100000
	v_lshl_add_u64 v[220:221], s[52:53], 0, v[178:179]
	s_addc_u32 s91, s53, 0
	s_add_i32 s92, s66, s31
	global_load_lds_dwordx4 v[220:221], off
	v_lshl_add_u64 v[228:229], s[90:91], 0, v[182:183]
	s_mov_b32 m0, s92
	v_lshl_add_u64 v[230:231], s[54:55], 0, v[180:181]
	global_load_lds_dwordx4 v[228:229], off
	v_lshl_add_u64 v[228:229], s[90:91], 0, v[178:179]
	s_add_i32 m0, s92, 0x2000
	s_nop 0
	global_load_lds_dwordx4 v[228:229], off
	v_lshl_add_u64 v[228:229], s[54:55], 0, v[184:185]
	s_mov_b32 m0, s56
	s_nop 0
	global_load_lds_dwordx4 v[228:229], off
	s_mov_b32 m0, s57
	s_nop 0
	global_load_lds_dwordx4 v[230:231], off
	s_waitcnt vmcnt(8)
	s_waitcnt lgkmcnt(0)
	s_setprio 1
	s_barrier
	v_mfma_f32_16x16x32_bf16 v[62:65], v[130:133], v[162:165], v[62:65]
	v_mfma_f32_16x16x32_bf16 v[58:61], v[138:141], v[162:165], v[58:61]
	v_mfma_f32_16x16x32_bf16 v[50:53], v[130:133], v[170:173], v[50:53]
	v_mfma_f32_16x16x32_bf16 v[42:45], v[138:141], v[170:173], v[42:45]
	v_mfma_f32_16x16x32_bf16 v[34:37], v[130:133], v[200:203], v[34:37]
	v_mfma_f32_16x16x32_bf16 v[26:29], v[138:141], v[200:203], v[26:29]
	v_mfma_f32_16x16x32_bf16 v[18:21], v[130:133], v[216:219], v[18:21]
	v_mfma_f32_16x16x32_bf16 v[10:13], v[138:141], v[216:219], v[10:13]
	v_mfma_f32_16x16x32_bf16 v[62:65], v[134:137], v[166:169], v[62:65]
	v_mfma_f32_16x16x32_bf16 v[58:61], v[142:145], v[166:169], v[58:61]
	v_mfma_f32_16x16x32_bf16 v[50:53], v[134:137], v[174:177], v[50:53]
	v_mfma_f32_16x16x32_bf16 v[42:45], v[142:145], v[174:177], v[42:45]
	v_mfma_f32_16x16x32_bf16 v[34:37], v[134:137], v[212:215], v[34:37]
	v_mfma_f32_16x16x32_bf16 v[26:29], v[142:145], v[212:215], v[26:29]
	v_mfma_f32_16x16x32_bf16 v[18:21], v[134:137], v[224:227], v[18:21]
	v_mfma_f32_16x16x32_bf16 v[10:13], v[142:145], v[224:227], v[10:13]
	s_setprio 0
	s_setprio 1
	v_mfma_f32_16x16x32_bf16 v[54:57], v[146:149], v[162:165], v[54:57]
	v_mfma_f32_16x16x32_bf16 v[46:49], v[154:157], v[162:165], v[46:49]
	v_mfma_f32_16x16x32_bf16 v[38:41], v[146:149], v[170:173], v[38:41]
	v_mfma_f32_16x16x32_bf16 v[30:33], v[154:157], v[170:173], v[30:33]
	v_mfma_f32_16x16x32_bf16 v[22:25], v[146:149], v[200:203], v[22:25]
	v_mfma_f32_16x16x32_bf16 v[14:17], v[154:157], v[200:203], v[14:17]
	v_mfma_f32_16x16x32_bf16 v[6:9], v[146:149], v[216:219], v[6:9]
	v_mfma_f32_16x16x32_bf16 v[2:5], v[154:157], v[216:219], v[2:5]
	v_mfma_f32_16x16x32_bf16 v[54:57], v[150:153], v[166:169], v[54:57]
	v_mfma_f32_16x16x32_bf16 v[46:49], v[158:161], v[166:169], v[46:49]
	v_mfma_f32_16x16x32_bf16 v[38:41], v[150:153], v[174:177], v[38:41]
	v_mfma_f32_16x16x32_bf16 v[30:33], v[158:161], v[174:177], v[30:33]
	v_mfma_f32_16x16x32_bf16 v[22:25], v[150:153], v[212:215], v[22:25]
	v_mfma_f32_16x16x32_bf16 v[14:17], v[158:161], v[212:215], v[14:17]
	v_mfma_f32_16x16x32_bf16 v[6:9], v[150:153], v[224:227], v[6:9]
	v_mfma_f32_16x16x32_bf16 v[2:5], v[158:161], v[224:227], v[2:5]
	s_barrier
	s_setprio 0
	s_add_i32 s90, 0, 0x18000
	s_add_i32 s91, 0, 0x1c000
	v_add_u32_e32 v142, s90, v189
	v_add_u32_e32 v158, s91, v189
	ds_read_b128 v[130:133], v142
	ds_read_b128 v[134:137], v142 offset:1024
	ds_read_b128 v[138:141], v142 offset:2048
	ds_read_b128 v[142:145], v142 offset:3072
	ds_read_b128 v[146:149], v158
	ds_read_b128 v[150:153], v158 offset:1024
	ds_read_b128 v[154:157], v158 offset:2048
	ds_read_b128 v[158:161], v158 offset:3072
	s_add_u32 s54, s54, 0x100000
	s_addc_u32 s55, s55, 0
	s_mov_b32 m0, s58
	v_lshl_add_u64 v[232:233], s[54:55], 0, v[184:185]
	ds_read_b128 v[162:165], v210 offset:32768
	ds_read_b128 v[166:169], v210 offset:33792
	ds_read_b128 v[170:173], v210 offset:34816
	ds_read_b128 v[174:177], v210 offset:35840
	ds_read_b128 v[200:203], v210 offset:36864
	ds_read_b128 v[212:215], v210 offset:37888
	ds_read_b128 v[216:219], v210 offset:38912
	ds_read_b128 v[224:227], v210 offset:39936
	global_load_lds_dwordx4 v[232:233], off
	v_lshl_add_u64 v[232:233], s[54:55], 0, v[180:181]
	s_mov_b32 m0, s59
	s_nop 0
	global_load_lds_dwordx4 v[232:233], off
	s_waitcnt vmcnt(8)
	s_waitcnt lgkmcnt(0)
	s_setprio 1
	s_barrier
	v_mfma_f32_16x16x32_bf16 v[126:129], v[130:133], v[162:165], v[126:129]
	v_mfma_f32_16x16x32_bf16 v[122:125], v[138:141], v[162:165], v[122:125]
	v_mfma_f32_16x16x32_bf16 v[110:113], v[130:133], v[170:173], v[110:113]
	v_mfma_f32_16x16x32_bf16 v[106:109], v[138:141], v[170:173], v[106:109]
	v_mfma_f32_16x16x32_bf16 v[94:97], v[130:133], v[200:203], v[94:97]
	v_mfma_f32_16x16x32_bf16 v[90:93], v[138:141], v[200:203], v[90:93]
	v_mfma_f32_16x16x32_bf16 v[78:81], v[130:133], v[216:219], v[78:81]
	v_mfma_f32_16x16x32_bf16 v[74:77], v[138:141], v[216:219], v[74:77]
	v_mfma_f32_16x16x32_bf16 v[126:129], v[134:137], v[166:169], v[126:129]
	v_mfma_f32_16x16x32_bf16 v[122:125], v[142:145], v[166:169], v[122:125]
	v_mfma_f32_16x16x32_bf16 v[110:113], v[134:137], v[174:177], v[110:113]
	v_mfma_f32_16x16x32_bf16 v[106:109], v[142:145], v[174:177], v[106:109]
	v_mfma_f32_16x16x32_bf16 v[94:97], v[134:137], v[212:215], v[94:97]
	v_mfma_f32_16x16x32_bf16 v[90:93], v[142:145], v[212:215], v[90:93]
	v_mfma_f32_16x16x32_bf16 v[78:81], v[134:137], v[224:227], v[78:81]
	v_mfma_f32_16x16x32_bf16 v[74:77], v[142:145], v[224:227], v[74:77]
	s_setprio 0
	s_setprio 1
	v_mfma_f32_16x16x32_bf16 v[118:121], v[146:149], v[162:165], v[118:121]
	v_mfma_f32_16x16x32_bf16 v[114:117], v[154:157], v[162:165], v[114:117]
	v_mfma_f32_16x16x32_bf16 v[102:105], v[146:149], v[170:173], v[102:105]
	v_mfma_f32_16x16x32_bf16 v[98:101], v[154:157], v[170:173], v[98:101]
	v_mfma_f32_16x16x32_bf16 v[86:89], v[146:149], v[200:203], v[86:89]
	v_mfma_f32_16x16x32_bf16 v[82:85], v[154:157], v[200:203], v[82:85]
	v_mfma_f32_16x16x32_bf16 v[70:73], v[146:149], v[216:219], v[70:73]
	v_mfma_f32_16x16x32_bf16 v[66:69], v[154:157], v[216:219], v[66:69]
	v_mfma_f32_16x16x32_bf16 v[118:121], v[150:153], v[166:169], v[118:121]
	v_mfma_f32_16x16x32_bf16 v[114:117], v[158:161], v[166:169], v[114:117]
	v_mfma_f32_16x16x32_bf16 v[102:105], v[150:153], v[174:177], v[102:105]
	v_mfma_f32_16x16x32_bf16 v[98:101], v[158:161], v[174:177], v[98:101]
	v_mfma_f32_16x16x32_bf16 v[86:89], v[150:153], v[212:215], v[86:89]
	v_mfma_f32_16x16x32_bf16 v[82:85], v[158:161], v[212:215], v[82:85]
	v_mfma_f32_16x16x32_bf16 v[70:73], v[150:153], v[224:227], v[70:73]
	v_mfma_f32_16x16x32_bf16 v[66:69], v[158:161], v[224:227], v[66:69]
	s_barrier
	s_setprio 0
	s_add_i32 s54, s90, s31
	v_lshl_add_u64 v[204:205], v[204:205], 0, s[8:9]
	s_mov_b32 m0, s54
	ds_read_b128 v[162:165], v210 offset:49152
	ds_read_b128 v[166:169], v210 offset:50176
	ds_read_b128 v[170:173], v210 offset:51200
	ds_read_b128 v[174:177], v210 offset:52224
	ds_read_b128 v[200:203], v210 offset:53248
	ds_read_b128 v[212:215], v210 offset:54272
	ds_read_b128 v[216:219], v210 offset:55296
	ds_read_b128 v[224:227], v210 offset:56320
	global_load_lds_dwordx4 v[204:205], off
	s_add_i32 m0, s54, 0x2000
	s_add_u32 s52, s52, 0x100080
	v_lshl_add_u64 v[204:205], v[220:221], 0, s[8:9]
	s_addc_u32 s53, s53, 0
	s_add_i32 s54, s91, s31
	global_load_lds_dwordx4 v[204:205], off
	v_lshl_add_u64 v[204:205], s[52:53], 0, v[182:183]
	s_mov_b32 m0, s54
	s_nop 0
	global_load_lds_dwordx4 v[204:205], off
	v_lshl_add_u64 v[204:205], s[52:53], 0, v[178:179]
	s_add_i32 m0, s54, 0x2000
	s_nop 0
	global_load_lds_dwordx4 v[204:205], off
	v_lshl_add_u64 v[204:205], v[228:229], 0, s[8:9]
	s_mov_b32 m0, s62
	s_nop 0
	global_load_lds_dwordx4 v[204:205], off
	v_lshl_add_u64 v[204:205], v[230:231], 0, s[8:9]
	s_mov_b32 m0, s63
	s_nop 0
	global_load_lds_dwordx4 v[204:205], off
	s_waitcnt vmcnt(8)
	s_waitcnt lgkmcnt(0)
	s_setprio 1
	s_barrier
	v_mfma_f32_16x16x32_bf16 v[62:65], v[130:133], v[162:165], v[62:65]
	v_mfma_f32_16x16x32_bf16 v[58:61], v[138:141], v[162:165], v[58:61]
	v_mfma_f32_16x16x32_bf16 v[50:53], v[130:133], v[170:173], v[50:53]
	v_mfma_f32_16x16x32_bf16 v[42:45], v[138:141], v[170:173], v[42:45]
	v_mfma_f32_16x16x32_bf16 v[34:37], v[130:133], v[200:203], v[34:37]
	v_mfma_f32_16x16x32_bf16 v[26:29], v[138:141], v[200:203], v[26:29]
	v_mfma_f32_16x16x32_bf16 v[18:21], v[130:133], v[216:219], v[18:21]
	v_mfma_f32_16x16x32_bf16 v[10:13], v[138:141], v[216:219], v[10:13]
	v_mfma_f32_16x16x32_bf16 v[62:65], v[134:137], v[166:169], v[62:65]
	v_mfma_f32_16x16x32_bf16 v[58:61], v[142:145], v[166:169], v[58:61]
	v_mfma_f32_16x16x32_bf16 v[50:53], v[134:137], v[174:177], v[50:53]
	v_mfma_f32_16x16x32_bf16 v[42:45], v[142:145], v[174:177], v[42:45]
	v_mfma_f32_16x16x32_bf16 v[34:37], v[134:137], v[212:215], v[34:37]
	v_mfma_f32_16x16x32_bf16 v[26:29], v[142:145], v[212:215], v[26:29]
	v_mfma_f32_16x16x32_bf16 v[18:21], v[134:137], v[224:227], v[18:21]
	v_mfma_f32_16x16x32_bf16 v[10:13], v[142:145], v[224:227], v[10:13]
	s_setprio 0
	s_setprio 1
	v_mfma_f32_16x16x32_bf16 v[54:57], v[146:149], v[162:165], v[54:57]
	v_mfma_f32_16x16x32_bf16 v[46:49], v[154:157], v[162:165], v[46:49]
	v_mfma_f32_16x16x32_bf16 v[38:41], v[146:149], v[170:173], v[38:41]
	v_mfma_f32_16x16x32_bf16 v[30:33], v[154:157], v[170:173], v[30:33]
	v_mfma_f32_16x16x32_bf16 v[22:25], v[146:149], v[200:203], v[22:25]
	v_mfma_f32_16x16x32_bf16 v[14:17], v[154:157], v[200:203], v[14:17]
	v_mfma_f32_16x16x32_bf16 v[6:9], v[146:149], v[216:219], v[6:9]
	v_mfma_f32_16x16x32_bf16 v[2:5], v[154:157], v[216:219], v[2:5]
	v_mfma_f32_16x16x32_bf16 v[54:57], v[150:153], v[166:169], v[54:57]
	v_mfma_f32_16x16x32_bf16 v[46:49], v[158:161], v[166:169], v[46:49]
	v_mfma_f32_16x16x32_bf16 v[38:41], v[150:153], v[174:177], v[38:41]
	v_mfma_f32_16x16x32_bf16 v[30:33], v[158:161], v[174:177], v[30:33]
	v_mfma_f32_16x16x32_bf16 v[22:25], v[150:153], v[212:215], v[22:25]
	v_mfma_f32_16x16x32_bf16 v[14:17], v[158:161], v[212:215], v[14:17]
	v_mfma_f32_16x16x32_bf16 v[6:9], v[150:153], v[224:227], v[6:9]
	v_mfma_f32_16x16x32_bf16 v[2:5], v[158:161], v[224:227], v[2:5]
	s_barrier
	s_setprio 0
	s_add_i32 s89, s89, 2
	s_add_u32 s50, s50, 0x100
	s_addc_u32 s51, s51, 0
	s_add_u32 s87, s87, 0x100
	s_addc_u32 s88, s88, 0
	s_cmp_gt_u32 s89, 61
	s_cbranch_scc0 .LBB0_224
	s_and_b64 vcc, exec, s[10:11]
	s_cbranch_vccz .LBB0_229
	s_barrier
	v_lshl_add_u32 v200, s0, 8, v1
	s_cmp_gt_i32 s84, 15
	s_mov_b64 s[50:51], -1
	s_cbranch_scc1 .LBB0_230

.LBB0_672:
	v_add_u32_e32 v142, s51, v220
	v_add_u32_e32 v158, s81, v220
	ds_read_b128 v[130:133], v142
	ds_read_b128 v[134:137], v142 offset:1024
	ds_read_b128 v[138:141], v142 offset:2048
	ds_read_b128 v[142:145], v142 offset:3072
	ds_read_b128 v[146:149], v158
	ds_read_b128 v[150:153], v158 offset:1024
	ds_read_b128 v[154:157], v158 offset:2048
	ds_read_b128 v[158:161], v158 offset:3072
	s_add_u32 s16, s0, 0xfff00080
	s_addc_u32 s17, s1, -1
	s_cmp_eq_u32 s26, 60
	s_cselect_b32 s19, s20, s17
	s_cselect_b32 s18, s21, s16
	s_cselect_b32 s17, s22, s25
	s_cselect_b32 s16, s23, s24
	v_lshl_add_u64 v[218:219], s[0:1], 0, v[194:195]
	s_add_i32 m0, s31, 0xc000
	ds_read_b128 v[162:165], v233
	ds_read_b128 v[166:169], v233 offset:1024
	ds_read_b128 v[170:173], v233 offset:2048
	ds_read_b128 v[174:177], v233 offset:3072
	ds_read_b128 v[202:205], v233 offset:4096
	ds_read_b128 v[206:209], v233 offset:5120
	ds_read_b128 v[210:213], v233 offset:6144
	ds_read_b128 v[214:217], v233 offset:7168
	global_load_lds_dwordx4 v[218:219], off
	v_lshl_add_u64 v[218:219], s[0:1], 0, v[196:197]
	s_add_i32 m0, s31, 0xe000
	s_nop 0
	global_load_lds_dwordx4 v[218:219], off
	s_waitcnt vmcnt(8)
	s_waitcnt lgkmcnt(0)
	s_setprio 1
	s_barrier
	v_mfma_f32_16x16x32_bf16 v[90:93], v[130:133], v[162:165], v[90:93]
	v_mfma_f32_16x16x32_bf16 v[58:61], v[138:141], v[162:165], v[58:61]
	v_mfma_f32_16x16x32_bf16 v[98:101], v[130:133], v[170:173], v[98:101]
	v_mfma_f32_16x16x32_bf16 v[66:69], v[138:141], v[170:173], v[66:69]
	v_mfma_f32_16x16x32_bf16 v[102:105], v[130:133], v[202:205], v[102:105]
	v_mfma_f32_16x16x32_bf16 v[70:73], v[138:141], v[202:205], v[70:73]
	v_mfma_f32_16x16x32_bf16 v[110:113], v[130:133], v[210:213], v[110:113]
	v_mfma_f32_16x16x32_bf16 v[78:81], v[138:141], v[210:213], v[78:81]
	v_mfma_f32_16x16x32_bf16 v[90:93], v[134:137], v[166:169], v[90:93]
	v_mfma_f32_16x16x32_bf16 v[58:61], v[142:145], v[166:169], v[58:61]
	v_mfma_f32_16x16x32_bf16 v[98:101], v[134:137], v[174:177], v[98:101]
	v_mfma_f32_16x16x32_bf16 v[66:69], v[142:145], v[174:177], v[66:69]
	v_mfma_f32_16x16x32_bf16 v[102:105], v[134:137], v[206:209], v[102:105]
	v_mfma_f32_16x16x32_bf16 v[70:73], v[142:145], v[206:209], v[70:73]
	v_mfma_f32_16x16x32_bf16 v[110:113], v[134:137], v[214:217], v[110:113]
	v_mfma_f32_16x16x32_bf16 v[78:81], v[142:145], v[214:217], v[78:81]
	s_setprio 0
	s_setprio 1
	v_mfma_f32_16x16x32_bf16 v[26:29], v[146:149], v[162:165], v[26:29]
	v_mfma_f32_16x16x32_bf16 v[2:5], v[154:157], v[162:165], v[2:5]
	v_mfma_f32_16x16x32_bf16 v[34:37], v[146:149], v[170:173], v[34:37]
	v_mfma_f32_16x16x32_bf16 v[6:9], v[154:157], v[170:173], v[6:9]
	v_mfma_f32_16x16x32_bf16 v[38:41], v[146:149], v[202:205], v[38:41]
	v_mfma_f32_16x16x32_bf16 v[10:13], v[154:157], v[202:205], v[10:13]
	v_mfma_f32_16x16x32_bf16 v[46:49], v[146:149], v[210:213], v[46:49]
	v_mfma_f32_16x16x32_bf16 v[14:17], v[154:157], v[210:213], v[14:17]
	v_mfma_f32_16x16x32_bf16 v[26:29], v[150:153], v[166:169], v[26:29]
	v_mfma_f32_16x16x32_bf16 v[2:5], v[158:161], v[166:169], v[2:5]
	v_mfma_f32_16x16x32_bf16 v[34:37], v[150:153], v[174:177], v[34:37]
	v_mfma_f32_16x16x32_bf16 v[6:9], v[158:161], v[174:177], v[6:9]
	v_mfma_f32_16x16x32_bf16 v[38:41], v[150:153], v[206:209], v[38:41]
	v_mfma_f32_16x16x32_bf16 v[10:13], v[158:161], v[206:209], v[10:13]
	v_mfma_f32_16x16x32_bf16 v[46:49], v[150:153], v[214:217], v[46:49]
	v_mfma_f32_16x16x32_bf16 v[14:17], v[158:161], v[214:217], v[14:17]
	s_barrier
	s_setprio 0
	s_add_i32 s27, s51, s15
	v_lshl_add_u64 v[218:219], s[16:17], 0, v[178:179]
	s_mov_b32 m0, s27
	ds_read_b128 v[162:165], v233 offset:16384
	ds_read_b128 v[166:169], v233 offset:17408
	ds_read_b128 v[170:173], v233 offset:18432
	ds_read_b128 v[174:177], v233 offset:19456
	ds_read_b128 v[202:205], v233 offset:20480
	ds_read_b128 v[206:209], v233 offset:21504
	ds_read_b128 v[210:213], v233 offset:22528
	ds_read_b128 v[214:217], v233 offset:23552
	global_load_lds_dwordx4 v[218:219], off
	s_add_i32 m0, s27, 0x2000
	s_add_u32 s62, s16, 0x100000
	v_lshl_add_u64 v[242:243], s[16:17], 0, v[180:181]
	s_addc_u32 s63, s17, 0
	s_add_i32 s27, s81, s15
	global_load_lds_dwordx4 v[242:243], off
	v_lshl_add_u64 v[244:245], s[62:63], 0, v[178:179]
	s_mov_b32 m0, s27
	v_lshl_add_u64 v[246:247], s[18:19], 0, v[180:181]
	global_load_lds_dwordx4 v[244:245], off
	v_lshl_add_u64 v[244:245], s[62:63], 0, v[180:181]
	s_add_i32 m0, s27, 0x2000
	s_nop 0
	global_load_lds_dwordx4 v[244:245], off
	v_lshl_add_u64 v[244:245], s[18:19], 0, v[178:179]
	s_mov_b32 m0, s31
	s_nop 0
	global_load_lds_dwordx4 v[244:245], off
	s_mov_b32 m0, s34
	s_nop 0
	global_load_lds_dwordx4 v[246:247], off
	s_waitcnt vmcnt(8)
	s_waitcnt lgkmcnt(0)
	s_setprio 1
	s_barrier
	v_mfma_f32_16x16x32_bf16 v[114:117], v[130:133], v[162:165], v[114:117]
	v_mfma_f32_16x16x32_bf16 v[82:85], v[138:141], v[162:165], v[82:85]
	v_mfma_f32_16x16x32_bf16 v[118:121], v[130:133], v[170:173], v[118:121]
	v_mfma_f32_16x16x32_bf16 v[86:89], v[138:141], v[170:173], v[86:89]
	v_mfma_f32_16x16x32_bf16 v[122:125], v[130:133], v[202:205], v[122:125]
	v_mfma_f32_16x16x32_bf16 v[94:97], v[138:141], v[202:205], v[94:97]
	v_mfma_f32_16x16x32_bf16 v[126:129], v[130:133], v[210:213], v[126:129]
	v_mfma_f32_16x16x32_bf16 v[106:109], v[138:141], v[210:213], v[106:109]
	v_mfma_f32_16x16x32_bf16 v[114:117], v[134:137], v[166:169], v[114:117]
	v_mfma_f32_16x16x32_bf16 v[82:85], v[142:145], v[166:169], v[82:85]
	v_mfma_f32_16x16x32_bf16 v[118:121], v[134:137], v[174:177], v[118:121]
	v_mfma_f32_16x16x32_bf16 v[86:89], v[142:145], v[174:177], v[86:89]
	v_mfma_f32_16x16x32_bf16 v[122:125], v[134:137], v[206:209], v[122:125]
	v_mfma_f32_16x16x32_bf16 v[94:97], v[142:145], v[206:209], v[94:97]
	v_mfma_f32_16x16x32_bf16 v[126:129], v[134:137], v[214:217], v[126:129]
	v_mfma_f32_16x16x32_bf16 v[106:109], v[142:145], v[214:217], v[106:109]
	s_setprio 0
	s_setprio 1
	v_mfma_f32_16x16x32_bf16 v[50:53], v[146:149], v[162:165], v[50:53]
	v_mfma_f32_16x16x32_bf16 v[18:21], v[154:157], v[162:165], v[18:21]
	v_mfma_f32_16x16x32_bf16 v[54:57], v[146:149], v[170:173], v[54:57]
	v_mfma_f32_16x16x32_bf16 v[22:25], v[154:157], v[170:173], v[22:25]
	v_mfma_f32_16x16x32_bf16 v[62:65], v[146:149], v[202:205], v[62:65]
	v_mfma_f32_16x16x32_bf16 v[30:33], v[154:157], v[202:205], v[30:33]
	v_mfma_f32_16x16x32_bf16 v[74:77], v[146:149], v[210:213], v[74:77]
	v_mfma_f32_16x16x32_bf16 v[42:45], v[154:157], v[210:213], v[42:45]
	v_mfma_f32_16x16x32_bf16 v[50:53], v[150:153], v[166:169], v[50:53]
	v_mfma_f32_16x16x32_bf16 v[18:21], v[158:161], v[166:169], v[18:21]
	v_mfma_f32_16x16x32_bf16 v[54:57], v[150:153], v[174:177], v[54:57]
	v_mfma_f32_16x16x32_bf16 v[22:25], v[158:161], v[174:177], v[22:25]
	v_mfma_f32_16x16x32_bf16 v[62:65], v[150:153], v[206:209], v[62:65]
	v_mfma_f32_16x16x32_bf16 v[30:33], v[158:161], v[206:209], v[30:33]
	v_mfma_f32_16x16x32_bf16 v[74:77], v[150:153], v[214:217], v[74:77]
	v_mfma_f32_16x16x32_bf16 v[42:45], v[158:161], v[214:217], v[42:45]
	s_barrier
	s_setprio 0
	s_add_i32 s27, 0, 0x18000
	s_add_i32 s59, 0, 0x1c000
	v_add_u32_e32 v142, s27, v220
	v_add_u32_e32 v158, s59, v220
	ds_read_b128 v[130:133], v142
	ds_read_b128 v[134:137], v142 offset:1024
	ds_read_b128 v[138:141], v142 offset:2048
	ds_read_b128 v[142:145], v142 offset:3072
	ds_read_b128 v[146:149], v158
	ds_read_b128 v[150:153], v158 offset:1024
	ds_read_b128 v[154:157], v158 offset:2048
	ds_read_b128 v[158:161], v158 offset:3072
	s_add_u32 s18, s18, 0x100000
	s_addc_u32 s19, s19, 0
	s_mov_b32 m0, s35
	v_lshl_add_u64 v[248:249], s[18:19], 0, v[178:179]
	ds_read_b128 v[162:165], v233 offset:32768
	ds_read_b128 v[166:169], v233 offset:33792
	ds_read_b128 v[170:173], v233 offset:34816
	ds_read_b128 v[174:177], v233 offset:35840
	ds_read_b128 v[202:205], v233 offset:36864
	ds_read_b128 v[206:209], v233 offset:37888
	ds_read_b128 v[210:213], v233 offset:38912
	ds_read_b128 v[214:217], v233 offset:39936
	global_load_lds_dwordx4 v[248:249], off
	v_lshl_add_u64 v[248:249], s[18:19], 0, v[180:181]
	s_mov_b32 m0, s86
	s_nop 0
	global_load_lds_dwordx4 v[248:249], off
	s_waitcnt vmcnt(8)
	s_waitcnt lgkmcnt(0)
	s_setprio 1
	s_barrier
	v_mfma_f32_16x16x32_bf16 v[90:93], v[130:133], v[162:165], v[90:93]
	v_mfma_f32_16x16x32_bf16 v[58:61], v[138:141], v[162:165], v[58:61]
	v_mfma_f32_16x16x32_bf16 v[98:101], v[130:133], v[170:173], v[98:101]
	v_mfma_f32_16x16x32_bf16 v[66:69], v[138:141], v[170:173], v[66:69]
	v_mfma_f32_16x16x32_bf16 v[102:105], v[130:133], v[202:205], v[102:105]
	v_mfma_f32_16x16x32_bf16 v[70:73], v[138:141], v[202:205], v[70:73]
	v_mfma_f32_16x16x32_bf16 v[110:113], v[130:133], v[210:213], v[110:113]
	v_mfma_f32_16x16x32_bf16 v[78:81], v[138:141], v[210:213], v[78:81]
	v_mfma_f32_16x16x32_bf16 v[90:93], v[134:137], v[166:169], v[90:93]
	v_mfma_f32_16x16x32_bf16 v[58:61], v[142:145], v[166:169], v[58:61]
	v_mfma_f32_16x16x32_bf16 v[98:101], v[134:137], v[174:177], v[98:101]
	v_mfma_f32_16x16x32_bf16 v[66:69], v[142:145], v[174:177], v[66:69]
	v_mfma_f32_16x16x32_bf16 v[102:105], v[134:137], v[206:209], v[102:105]
	v_mfma_f32_16x16x32_bf16 v[70:73], v[142:145], v[206:209], v[70:73]
	v_mfma_f32_16x16x32_bf16 v[110:113], v[134:137], v[214:217], v[110:113]
	v_mfma_f32_16x16x32_bf16 v[78:81], v[142:145], v[214:217], v[78:81]
	s_setprio 0
	s_setprio 1
	v_mfma_f32_16x16x32_bf16 v[26:29], v[146:149], v[162:165], v[26:29]
	v_mfma_f32_16x16x32_bf16 v[2:5], v[154:157], v[162:165], v[2:5]
	v_mfma_f32_16x16x32_bf16 v[34:37], v[146:149], v[170:173], v[34:37]
	v_mfma_f32_16x16x32_bf16 v[6:9], v[154:157], v[170:173], v[6:9]
	v_mfma_f32_16x16x32_bf16 v[38:41], v[146:149], v[202:205], v[38:41]
	v_mfma_f32_16x16x32_bf16 v[10:13], v[154:157], v[202:205], v[10:13]
	v_mfma_f32_16x16x32_bf16 v[46:49], v[146:149], v[210:213], v[46:49]
	v_mfma_f32_16x16x32_bf16 v[14:17], v[154:157], v[210:213], v[14:17]
	v_mfma_f32_16x16x32_bf16 v[26:29], v[150:153], v[166:169], v[26:29]
	v_mfma_f32_16x16x32_bf16 v[2:5], v[158:161], v[166:169], v[2:5]
	v_mfma_f32_16x16x32_bf16 v[34:37], v[150:153], v[174:177], v[34:37]
	v_mfma_f32_16x16x32_bf16 v[6:9], v[158:161], v[174:177], v[6:9]
	v_mfma_f32_16x16x32_bf16 v[38:41], v[150:153], v[206:209], v[38:41]
	v_mfma_f32_16x16x32_bf16 v[10:13], v[158:161], v[206:209], v[10:13]
	v_mfma_f32_16x16x32_bf16 v[46:49], v[150:153], v[214:217], v[46:49]
	v_mfma_f32_16x16x32_bf16 v[14:17], v[158:161], v[214:217], v[14:17]
	s_barrier
	s_setprio 0
	s_add_i32 s18, s27, s15
	v_lshl_add_u64 v[218:219], v[218:219], 0, s[44:45]
	s_mov_b32 m0, s18
	ds_read_b128 v[162:165], v233 offset:49152
	ds_read_b128 v[166:169], v233 offset:50176
	ds_read_b128 v[170:173], v233 offset:51200
	ds_read_b128 v[174:177], v233 offset:52224
	ds_read_b128 v[202:205], v233 offset:53248
	ds_read_b128 v[206:209], v233 offset:54272
	ds_read_b128 v[210:213], v233 offset:55296
	ds_read_b128 v[214:217], v233 offset:56320
	global_load_lds_dwordx4 v[218:219], off
	s_add_i32 m0, s18, 0x2000
	s_add_u32 s16, s16, 0x100080
	v_lshl_add_u64 v[218:219], v[242:243], 0, s[44:45]
	s_addc_u32 s17, s17, 0
	s_add_i32 s18, s59, s15
	global_load_lds_dwordx4 v[218:219], off
	v_lshl_add_u64 v[218:219], s[16:17], 0, v[178:179]
	s_mov_b32 m0, s18
	s_nop 0
	global_load_lds_dwordx4 v[218:219], off
	v_lshl_add_u64 v[218:219], s[16:17], 0, v[180:181]
	s_add_i32 m0, s18, 0x2000
	s_nop 0
	global_load_lds_dwordx4 v[218:219], off
	v_lshl_add_u64 v[218:219], v[244:245], 0, s[44:45]
	s_mov_b32 m0, s66
	s_nop 0
	global_load_lds_dwordx4 v[218:219], off
	v_lshl_add_u64 v[218:219], v[246:247], 0, s[44:45]
	s_mov_b32 m0, s67
	s_nop 0
	global_load_lds_dwordx4 v[218:219], off
	s_waitcnt vmcnt(8)
	s_waitcnt lgkmcnt(0)
	s_setprio 1
	s_barrier
	v_mfma_f32_16x16x32_bf16 v[114:117], v[130:133], v[162:165], v[114:117]
	v_mfma_f32_16x16x32_bf16 v[82:85], v[138:141], v[162:165], v[82:85]
	v_mfma_f32_16x16x32_bf16 v[118:121], v[130:133], v[170:173], v[118:121]
	v_mfma_f32_16x16x32_bf16 v[86:89], v[138:141], v[170:173], v[86:89]
	v_mfma_f32_16x16x32_bf16 v[122:125], v[130:133], v[202:205], v[122:125]
	v_mfma_f32_16x16x32_bf16 v[94:97], v[138:141], v[202:205], v[94:97]
	v_mfma_f32_16x16x32_bf16 v[126:129], v[130:133], v[210:213], v[126:129]
	v_mfma_f32_16x16x32_bf16 v[106:109], v[138:141], v[210:213], v[106:109]
	v_mfma_f32_16x16x32_bf16 v[114:117], v[134:137], v[166:169], v[114:117]
	v_mfma_f32_16x16x32_bf16 v[82:85], v[142:145], v[166:169], v[82:85]
	v_mfma_f32_16x16x32_bf16 v[118:121], v[134:137], v[174:177], v[118:121]
	v_mfma_f32_16x16x32_bf16 v[86:89], v[142:145], v[174:177], v[86:89]
	v_mfma_f32_16x16x32_bf16 v[122:125], v[134:137], v[206:209], v[122:125]
	v_mfma_f32_16x16x32_bf16 v[94:97], v[142:145], v[206:209], v[94:97]
	v_mfma_f32_16x16x32_bf16 v[126:129], v[134:137], v[214:217], v[126:129]
	v_mfma_f32_16x16x32_bf16 v[106:109], v[142:145], v[214:217], v[106:109]
	s_setprio 0
	s_setprio 1
	v_mfma_f32_16x16x32_bf16 v[50:53], v[146:149], v[162:165], v[50:53]
	v_mfma_f32_16x16x32_bf16 v[18:21], v[154:157], v[162:165], v[18:21]
	v_mfma_f32_16x16x32_bf16 v[54:57], v[146:149], v[170:173], v[54:57]
	v_mfma_f32_16x16x32_bf16 v[22:25], v[154:157], v[170:173], v[22:25]
	v_mfma_f32_16x16x32_bf16 v[62:65], v[146:149], v[202:205], v[62:65]
	v_mfma_f32_16x16x32_bf16 v[30:33], v[154:157], v[202:205], v[30:33]
	v_mfma_f32_16x16x32_bf16 v[74:77], v[146:149], v[210:213], v[74:77]
	v_mfma_f32_16x16x32_bf16 v[42:45], v[154:157], v[210:213], v[42:45]
	v_mfma_f32_16x16x32_bf16 v[50:53], v[150:153], v[166:169], v[50:53]
	v_mfma_f32_16x16x32_bf16 v[18:21], v[158:161], v[166:169], v[18:21]
	v_mfma_f32_16x16x32_bf16 v[54:57], v[150:153], v[174:177], v[54:57]
	v_mfma_f32_16x16x32_bf16 v[22:25], v[158:161], v[174:177], v[22:25]
	v_mfma_f32_16x16x32_bf16 v[62:65], v[150:153], v[206:209], v[62:65]
	v_mfma_f32_16x16x32_bf16 v[30:33], v[158:161], v[206:209], v[30:33]
	v_mfma_f32_16x16x32_bf16 v[74:77], v[150:153], v[214:217], v[74:77]
	v_mfma_f32_16x16x32_bf16 v[42:45], v[158:161], v[214:217], v[42:45]
	s_barrier
	s_setprio 0
	s_add_i32 s26, s26, 2
	s_add_u32 s0, s0, 0x100
	s_addc_u32 s1, s1, 0
	s_add_u32 s24, s24, 0x100
	s_addc_u32 s25, s25, 0
	s_cmp_gt_u32 s26, 61
	s_cbranch_scc0 .LBB0_672
	s_and_b64 vcc, exec, s[90:91]
	s_cbranch_vccz .LBB0_675
	s_barrier

.LBB0_788:
	ds_read_b128 v[156:159], v153
	ds_read_b128 v[160:163], v153 offset:1024
	ds_read_b128 v[164:167], v153 offset:2048
	ds_read_b128 v[168:171], v153 offset:3072
	ds_read_b128 v[172:175], v154
	ds_read_b128 v[176:179], v154 offset:1024
	ds_read_b128 v[180:183], v154 offset:2048
	ds_read_b128 v[184:187], v154 offset:3072
	s_add_u32 s36, s26, 0xfff00080
	s_addc_u32 s37, s27, -1
	s_cmp_eq_u32 s54, 60
	s_cselect_b32 s39, s19, s37
	s_cselect_b32 s38, s50, s36
	s_cselect_b32 s37, s17, s53
	s_cselect_b32 s36, s51, s52
	v_lshl_add_u64 v[148:149], s[26:27], 0, v[140:141]
	s_add_i32 m0, s25, 0xc000
	ds_read_b128 v[188:191], v155
	ds_read_b128 v[192:195], v155 offset:1024
	ds_read_b128 v[196:199], v155 offset:2048
	ds_read_b128 v[200:203], v155 offset:3072
	ds_read_b128 v[204:207], v155 offset:4096
	ds_read_b128 v[208:211], v155 offset:5120
	ds_read_b128 v[212:215], v155 offset:6144
	ds_read_b128 v[216:219], v155 offset:7168
	global_load_lds_dwordx4 v[148:149], off
	v_lshl_add_u64 v[148:149], s[26:27], 0, v[142:143]
	s_add_i32 m0, s25, 0xe000
	s_nop 0
	global_load_lds_dwordx4 v[148:149], off
	s_waitcnt vmcnt(8)
	s_waitcnt lgkmcnt(0)
	s_setprio 1
	s_barrier
	v_mfma_f32_16x16x32_bf16 v[126:129], v[156:159], v[188:191], v[126:129]
	v_mfma_f32_16x16x32_bf16 v[122:125], v[164:167], v[188:191], v[122:125]
	v_mfma_f32_16x16x32_bf16 v[118:121], v[156:159], v[196:199], v[118:121]
	v_mfma_f32_16x16x32_bf16 v[114:117], v[164:167], v[196:199], v[114:117]
	v_mfma_f32_16x16x32_bf16 v[94:97], v[156:159], v[204:207], v[94:97]
	v_mfma_f32_16x16x32_bf16 v[90:93], v[164:167], v[204:207], v[90:93]
	v_mfma_f32_16x16x32_bf16 v[86:89], v[156:159], v[212:215], v[86:89]
	v_mfma_f32_16x16x32_bf16 v[82:85], v[164:167], v[212:215], v[82:85]
	v_mfma_f32_16x16x32_bf16 v[126:129], v[160:163], v[192:195], v[126:129]
	v_mfma_f32_16x16x32_bf16 v[122:125], v[168:171], v[192:195], v[122:125]
	v_mfma_f32_16x16x32_bf16 v[118:121], v[160:163], v[200:203], v[118:121]
	v_mfma_f32_16x16x32_bf16 v[114:117], v[168:171], v[200:203], v[114:117]
	v_mfma_f32_16x16x32_bf16 v[94:97], v[160:163], v[208:211], v[94:97]
	v_mfma_f32_16x16x32_bf16 v[90:93], v[168:171], v[208:211], v[90:93]
	v_mfma_f32_16x16x32_bf16 v[86:89], v[160:163], v[216:219], v[86:89]
	v_mfma_f32_16x16x32_bf16 v[82:85], v[168:171], v[216:219], v[82:85]
	s_setprio 0
	s_setprio 1
	v_mfma_f32_16x16x32_bf16 v[110:113], v[172:175], v[188:191], v[110:113]
	v_mfma_f32_16x16x32_bf16 v[106:109], v[180:183], v[188:191], v[106:109]
	v_mfma_f32_16x16x32_bf16 v[102:105], v[172:175], v[196:199], v[102:105]
	v_mfma_f32_16x16x32_bf16 v[98:101], v[180:183], v[196:199], v[98:101]
	v_mfma_f32_16x16x32_bf16 v[78:81], v[172:175], v[204:207], v[78:81]
	v_mfma_f32_16x16x32_bf16 v[74:77], v[180:183], v[204:207], v[74:77]
	v_mfma_f32_16x16x32_bf16 v[70:73], v[172:175], v[212:215], v[70:73]
	v_mfma_f32_16x16x32_bf16 v[66:69], v[180:183], v[212:215], v[66:69]
	v_mfma_f32_16x16x32_bf16 v[110:113], v[176:179], v[192:195], v[110:113]
	v_mfma_f32_16x16x32_bf16 v[106:109], v[184:187], v[192:195], v[106:109]
	v_mfma_f32_16x16x32_bf16 v[102:105], v[176:179], v[200:203], v[102:105]
	v_mfma_f32_16x16x32_bf16 v[98:101], v[184:187], v[200:203], v[98:101]
	v_mfma_f32_16x16x32_bf16 v[78:81], v[176:179], v[208:211], v[78:81]
	v_mfma_f32_16x16x32_bf16 v[74:77], v[184:187], v[208:211], v[74:77]
	v_mfma_f32_16x16x32_bf16 v[70:73], v[176:179], v[216:219], v[70:73]
	v_mfma_f32_16x16x32_bf16 v[66:69], v[184:187], v[216:219], v[66:69]
	s_barrier
	s_setprio 0
	s_add_i32 s55, s44, s13
	v_lshl_add_u64 v[148:149], s[36:37], 0, v[134:135]
	s_mov_b32 m0, s55
	ds_read_b128 v[188:191], v155 offset:16384
	ds_read_b128 v[192:195], v155 offset:17408
	ds_read_b128 v[196:199], v155 offset:18432
	ds_read_b128 v[200:203], v155 offset:19456
	ds_read_b128 v[204:207], v155 offset:20480
	ds_read_b128 v[208:211], v155 offset:21504
	ds_read_b128 v[212:215], v155 offset:22528
	ds_read_b128 v[216:219], v155 offset:23552
	global_load_lds_dwordx4 v[148:149], off
	s_add_i32 m0, s55, 0x2000
	s_add_u32 s56, s36, 0x100000
	v_lshl_add_u64 v[220:221], s[36:37], 0, v[130:131]
	s_addc_u32 s57, s37, 0
	s_add_i32 s55, s45, s13
	global_load_lds_dwordx4 v[220:221], off
	v_lshl_add_u64 v[224:225], s[56:57], 0, v[134:135]
	s_mov_b32 m0, s55
	v_lshl_add_u64 v[226:227], s[38:39], 0, v[132:133]
	global_load_lds_dwordx4 v[224:225], off
	v_lshl_add_u64 v[224:225], s[56:57], 0, v[130:131]
	s_add_i32 m0, s55, 0x2000
	s_nop 0
	global_load_lds_dwordx4 v[224:225], off
	v_lshl_add_u64 v[224:225], s[38:39], 0, v[136:137]
	s_mov_b32 m0, s25
	s_nop 0
	global_load_lds_dwordx4 v[224:225], off
	s_mov_b32 m0, s31
	s_nop 0
	global_load_lds_dwordx4 v[226:227], off
	s_waitcnt vmcnt(8)
	s_waitcnt lgkmcnt(0)
	s_setprio 1
	s_barrier
	v_mfma_f32_16x16x32_bf16 v[62:65], v[156:159], v[188:191], v[62:65]
	v_mfma_f32_16x16x32_bf16 v[58:61], v[164:167], v[188:191], v[58:61]
	v_mfma_f32_16x16x32_bf16 v[54:57], v[156:159], v[196:199], v[54:57]
	v_mfma_f32_16x16x32_bf16 v[50:53], v[164:167], v[196:199], v[50:53]
	v_mfma_f32_16x16x32_bf16 v[30:33], v[156:159], v[204:207], v[30:33]
	v_mfma_f32_16x16x32_bf16 v[26:29], v[164:167], v[204:207], v[26:29]
	v_mfma_f32_16x16x32_bf16 v[22:25], v[156:159], v[212:215], v[22:25]
	v_mfma_f32_16x16x32_bf16 v[18:21], v[164:167], v[212:215], v[18:21]
	v_mfma_f32_16x16x32_bf16 v[62:65], v[160:163], v[192:195], v[62:65]
	v_mfma_f32_16x16x32_bf16 v[58:61], v[168:171], v[192:195], v[58:61]
	v_mfma_f32_16x16x32_bf16 v[54:57], v[160:163], v[200:203], v[54:57]
	v_mfma_f32_16x16x32_bf16 v[50:53], v[168:171], v[200:203], v[50:53]
	v_mfma_f32_16x16x32_bf16 v[30:33], v[160:163], v[208:211], v[30:33]
	v_mfma_f32_16x16x32_bf16 v[26:29], v[168:171], v[208:211], v[26:29]
	v_mfma_f32_16x16x32_bf16 v[22:25], v[160:163], v[216:219], v[22:25]
	v_mfma_f32_16x16x32_bf16 v[18:21], v[168:171], v[216:219], v[18:21]
	s_setprio 0
	s_setprio 1
	v_mfma_f32_16x16x32_bf16 v[46:49], v[172:175], v[188:191], v[46:49]
	v_mfma_f32_16x16x32_bf16 v[42:45], v[180:183], v[188:191], v[42:45]
	v_mfma_f32_16x16x32_bf16 v[38:41], v[172:175], v[196:199], v[38:41]
	v_mfma_f32_16x16x32_bf16 v[34:37], v[180:183], v[196:199], v[34:37]
	v_mfma_f32_16x16x32_bf16 v[14:17], v[172:175], v[204:207], v[14:17]
	v_mfma_f32_16x16x32_bf16 v[10:13], v[180:183], v[204:207], v[10:13]
	v_mfma_f32_16x16x32_bf16 v[6:9], v[172:175], v[212:215], v[6:9]
	v_mfma_f32_16x16x32_bf16 v[2:5], v[180:183], v[212:215], v[2:5]
	v_mfma_f32_16x16x32_bf16 v[46:49], v[176:179], v[192:195], v[46:49]
	v_mfma_f32_16x16x32_bf16 v[42:45], v[184:187], v[192:195], v[42:45]
	v_mfma_f32_16x16x32_bf16 v[38:41], v[176:179], v[200:203], v[38:41]
	v_mfma_f32_16x16x32_bf16 v[34:37], v[184:187], v[200:203], v[34:37]
	v_mfma_f32_16x16x32_bf16 v[14:17], v[176:179], v[208:211], v[14:17]
	v_mfma_f32_16x16x32_bf16 v[10:13], v[184:187], v[208:211], v[10:13]
	v_mfma_f32_16x16x32_bf16 v[6:9], v[176:179], v[216:219], v[6:9]
	v_mfma_f32_16x16x32_bf16 v[2:5], v[184:187], v[216:219], v[2:5]
	s_barrier
	s_setprio 0
	s_add_i32 s55, 0, 0x18000
	s_add_i32 s56, 0, 0x1c000
	v_add_u32_e32 v168, s55, v151
	v_add_u32_e32 v184, s56, v151
	ds_read_b128 v[156:159], v168
	ds_read_b128 v[160:163], v168 offset:1024
	ds_read_b128 v[164:167], v168 offset:2048
	ds_read_b128 v[168:171], v168 offset:3072
	ds_read_b128 v[172:175], v184
	ds_read_b128 v[176:179], v184 offset:1024
	ds_read_b128 v[180:183], v184 offset:2048
	ds_read_b128 v[184:187], v184 offset:3072
	s_add_u32 s38, s38, 0x100000
	s_addc_u32 s39, s39, 0
	s_mov_b32 m0, s34
	v_lshl_add_u64 v[228:229], s[38:39], 0, v[136:137]
	ds_read_b128 v[188:191], v155 offset:32768
	ds_read_b128 v[192:195], v155 offset:33792
	ds_read_b128 v[196:199], v155 offset:34816
	ds_read_b128 v[200:203], v155 offset:35840
	ds_read_b128 v[204:207], v155 offset:36864
	ds_read_b128 v[208:211], v155 offset:37888
	ds_read_b128 v[212:215], v155 offset:38912
	ds_read_b128 v[216:219], v155 offset:39936
	global_load_lds_dwordx4 v[228:229], off
	v_lshl_add_u64 v[228:229], s[38:39], 0, v[132:133]
	s_mov_b32 m0, s35
	s_nop 0
	global_load_lds_dwordx4 v[228:229], off
	s_waitcnt vmcnt(8)
	s_waitcnt lgkmcnt(0)
	s_setprio 1
	s_barrier
	v_mfma_f32_16x16x32_bf16 v[126:129], v[156:159], v[188:191], v[126:129]
	v_mfma_f32_16x16x32_bf16 v[122:125], v[164:167], v[188:191], v[122:125]
	v_mfma_f32_16x16x32_bf16 v[118:121], v[156:159], v[196:199], v[118:121]
	v_mfma_f32_16x16x32_bf16 v[114:117], v[164:167], v[196:199], v[114:117]
	v_mfma_f32_16x16x32_bf16 v[94:97], v[156:159], v[204:207], v[94:97]
	v_mfma_f32_16x16x32_bf16 v[90:93], v[164:167], v[204:207], v[90:93]
	v_mfma_f32_16x16x32_bf16 v[86:89], v[156:159], v[212:215], v[86:89]
	v_mfma_f32_16x16x32_bf16 v[82:85], v[164:167], v[212:215], v[82:85]
	v_mfma_f32_16x16x32_bf16 v[126:129], v[160:163], v[192:195], v[126:129]
	v_mfma_f32_16x16x32_bf16 v[122:125], v[168:171], v[192:195], v[122:125]
	v_mfma_f32_16x16x32_bf16 v[118:121], v[160:163], v[200:203], v[118:121]
	v_mfma_f32_16x16x32_bf16 v[114:117], v[168:171], v[200:203], v[114:117]
	v_mfma_f32_16x16x32_bf16 v[94:97], v[160:163], v[208:211], v[94:97]
	v_mfma_f32_16x16x32_bf16 v[90:93], v[168:171], v[208:211], v[90:93]
	v_mfma_f32_16x16x32_bf16 v[86:89], v[160:163], v[216:219], v[86:89]
	v_mfma_f32_16x16x32_bf16 v[82:85], v[168:171], v[216:219], v[82:85]
	s_setprio 0
	s_setprio 1
	v_mfma_f32_16x16x32_bf16 v[110:113], v[172:175], v[188:191], v[110:113]
	v_mfma_f32_16x16x32_bf16 v[106:109], v[180:183], v[188:191], v[106:109]
	v_mfma_f32_16x16x32_bf16 v[102:105], v[172:175], v[196:199], v[102:105]
	v_mfma_f32_16x16x32_bf16 v[98:101], v[180:183], v[196:199], v[98:101]
	v_mfma_f32_16x16x32_bf16 v[78:81], v[172:175], v[204:207], v[78:81]
	v_mfma_f32_16x16x32_bf16 v[74:77], v[180:183], v[204:207], v[74:77]
	v_mfma_f32_16x16x32_bf16 v[70:73], v[172:175], v[212:215], v[70:73]
	v_mfma_f32_16x16x32_bf16 v[66:69], v[180:183], v[212:215], v[66:69]
	v_mfma_f32_16x16x32_bf16 v[110:113], v[176:179], v[192:195], v[110:113]
	v_mfma_f32_16x16x32_bf16 v[106:109], v[184:187], v[192:195], v[106:109]
	v_mfma_f32_16x16x32_bf16 v[102:105], v[176:179], v[200:203], v[102:105]
	v_mfma_f32_16x16x32_bf16 v[98:101], v[184:187], v[200:203], v[98:101]
	v_mfma_f32_16x16x32_bf16 v[78:81], v[176:179], v[208:211], v[78:81]
	v_mfma_f32_16x16x32_bf16 v[74:77], v[184:187], v[208:211], v[74:77]
	v_mfma_f32_16x16x32_bf16 v[70:73], v[176:179], v[216:219], v[70:73]
	v_mfma_f32_16x16x32_bf16 v[66:69], v[184:187], v[216:219], v[66:69]
	s_barrier
	s_setprio 0
	s_add_i32 s38, s55, s13
	v_lshl_add_u64 v[148:149], v[148:149], 0, s[6:7]
	s_mov_b32 m0, s38
	ds_read_b128 v[188:191], v155 offset:49152
	ds_read_b128 v[192:195], v155 offset:50176
	ds_read_b128 v[196:199], v155 offset:51200
	ds_read_b128 v[200:203], v155 offset:52224
	ds_read_b128 v[204:207], v155 offset:53248
	ds_read_b128 v[208:211], v155 offset:54272
	ds_read_b128 v[212:215], v155 offset:55296
	ds_read_b128 v[216:219], v155 offset:56320
	global_load_lds_dwordx4 v[148:149], off
	s_add_i32 m0, s38, 0x2000
	s_add_u32 s36, s36, 0x100080
	v_lshl_add_u64 v[148:149], v[220:221], 0, s[6:7]
	s_addc_u32 s37, s37, 0
	s_add_i32 s38, s56, s13
	global_load_lds_dwordx4 v[148:149], off
	v_lshl_add_u64 v[148:149], s[36:37], 0, v[134:135]
	s_mov_b32 m0, s38
	s_nop 0
	global_load_lds_dwordx4 v[148:149], off
	v_lshl_add_u64 v[148:149], s[36:37], 0, v[130:131]
	s_add_i32 m0, s38, 0x2000
	s_nop 0
	global_load_lds_dwordx4 v[148:149], off
	v_lshl_add_u64 v[148:149], v[224:225], 0, s[6:7]
	s_mov_b32 m0, s41
	s_nop 0
	global_load_lds_dwordx4 v[148:149], off
	v_lshl_add_u64 v[148:149], v[226:227], 0, s[6:7]
	s_mov_b32 m0, s42
	s_nop 0
	global_load_lds_dwordx4 v[148:149], off
	s_waitcnt vmcnt(8)
	s_waitcnt lgkmcnt(0)
	s_setprio 1
	s_barrier
	v_mfma_f32_16x16x32_bf16 v[62:65], v[156:159], v[188:191], v[62:65]
	v_mfma_f32_16x16x32_bf16 v[58:61], v[164:167], v[188:191], v[58:61]
	v_mfma_f32_16x16x32_bf16 v[54:57], v[156:159], v[196:199], v[54:57]
	v_mfma_f32_16x16x32_bf16 v[50:53], v[164:167], v[196:199], v[50:53]
	v_mfma_f32_16x16x32_bf16 v[30:33], v[156:159], v[204:207], v[30:33]
	v_mfma_f32_16x16x32_bf16 v[26:29], v[164:167], v[204:207], v[26:29]
	v_mfma_f32_16x16x32_bf16 v[22:25], v[156:159], v[212:215], v[22:25]
	v_mfma_f32_16x16x32_bf16 v[18:21], v[164:167], v[212:215], v[18:21]
	v_mfma_f32_16x16x32_bf16 v[62:65], v[160:163], v[192:195], v[62:65]
	v_mfma_f32_16x16x32_bf16 v[58:61], v[168:171], v[192:195], v[58:61]
	v_mfma_f32_16x16x32_bf16 v[54:57], v[160:163], v[200:203], v[54:57]
	v_mfma_f32_16x16x32_bf16 v[50:53], v[168:171], v[200:203], v[50:53]
	v_mfma_f32_16x16x32_bf16 v[30:33], v[160:163], v[208:211], v[30:33]
	v_mfma_f32_16x16x32_bf16 v[26:29], v[168:171], v[208:211], v[26:29]
	v_mfma_f32_16x16x32_bf16 v[22:25], v[160:163], v[216:219], v[22:25]
	v_mfma_f32_16x16x32_bf16 v[18:21], v[168:171], v[216:219], v[18:21]
	s_setprio 0
	s_setprio 1
	v_mfma_f32_16x16x32_bf16 v[46:49], v[172:175], v[188:191], v[46:49]
	v_mfma_f32_16x16x32_bf16 v[42:45], v[180:183], v[188:191], v[42:45]
	v_mfma_f32_16x16x32_bf16 v[38:41], v[172:175], v[196:199], v[38:41]
	v_mfma_f32_16x16x32_bf16 v[34:37], v[180:183], v[196:199], v[34:37]
	v_mfma_f32_16x16x32_bf16 v[14:17], v[172:175], v[204:207], v[14:17]
	v_mfma_f32_16x16x32_bf16 v[10:13], v[180:183], v[204:207], v[10:13]
	v_mfma_f32_16x16x32_bf16 v[6:9], v[172:175], v[212:215], v[6:9]
	v_mfma_f32_16x16x32_bf16 v[2:5], v[180:183], v[212:215], v[2:5]
	v_mfma_f32_16x16x32_bf16 v[46:49], v[176:179], v[192:195], v[46:49]
	v_mfma_f32_16x16x32_bf16 v[42:45], v[184:187], v[192:195], v[42:45]
	v_mfma_f32_16x16x32_bf16 v[38:41], v[176:179], v[200:203], v[38:41]
	v_mfma_f32_16x16x32_bf16 v[34:37], v[184:187], v[200:203], v[34:37]
	v_mfma_f32_16x16x32_bf16 v[14:17], v[176:179], v[208:211], v[14:17]
	v_mfma_f32_16x16x32_bf16 v[10:13], v[184:187], v[208:211], v[10:13]
	v_mfma_f32_16x16x32_bf16 v[6:9], v[176:179], v[216:219], v[6:9]
	v_mfma_f32_16x16x32_bf16 v[2:5], v[184:187], v[216:219], v[2:5]
	s_barrier
	s_setprio 0
	s_add_i32 s54, s54, 2
	s_add_u32 s26, s26, 0x100
	s_addc_u32 s27, s27, 0
	s_add_u32 s52, s52, 0x100
	s_addc_u32 s53, s53, 0
	s_cmp_gt_u32 s54, 61
	s_cbranch_scc0 .LBB0_788
	s_and_b64 vcc, exec, s[8:9]
	s_cbranch_vccz .LBB0_791
	s_barrier

.LBB0_1040:
	ds_read_b128 v[130:133], v207
	ds_read_b128 v[134:137], v207 offset:1024
	ds_read_b128 v[138:141], v207 offset:2048
	ds_read_b128 v[142:145], v207 offset:3072
	ds_read_b128 v[146:149], v208
	ds_read_b128 v[172:175], v208 offset:1024
	ds_read_b128 v[176:179], v208 offset:2048
	ds_read_b128 v[210:213], v208 offset:3072
	s_add_u32 s10, s8, 0xffd50080
	s_addc_u32 s11, s9, -1
	s_cmpk_eq_i32 s16, 0xa8
	s_cselect_b32 s13, s25, s11
	s_cselect_b32 s12, s24, s10
	s_cselect_b32 s11, s41, s15
	s_cselect_b32 s10, s40, s14
	v_lshl_add_u64 v[180:181], s[8:9], 0, v[166:167]
	s_add_i32 m0, s48, 0xc000
	ds_read_b128 v[214:217], v202
	ds_read_b128 v[218:221], v202 offset:1024
	ds_read_b128 v[224:227], v202 offset:2048
	ds_read_b128 v[228:231], v202 offset:3072
	ds_read_b128 v[232:235], v202 offset:4096
	ds_read_b128 v[236:239], v202 offset:5120
	ds_read_b128 v[240:243], v202 offset:6144
	ds_read_b128 v[244:247], v202 offset:7168
	global_load_lds_dwordx4 v[180:181], off
	v_lshl_add_u64 v[180:181], s[8:9], 0, v[168:169]
	s_add_i32 m0, s48, 0xe000
	s_nop 0
	global_load_lds_dwordx4 v[180:181], off
	s_waitcnt vmcnt(8)
	s_waitcnt lgkmcnt(0)
	s_setprio 1
	s_barrier
	v_mfma_f32_16x16x32_bf16 v[90:93], v[130:133], v[214:217], v[90:93]
	v_mfma_f32_16x16x32_bf16 v[74:77], v[138:141], v[214:217], v[74:77]
	v_mfma_f32_16x16x32_bf16 v[46:49], v[130:133], v[224:227], v[46:49]
	v_mfma_f32_16x16x32_bf16 v[42:45], v[138:141], v[224:227], v[42:45]
	v_mfma_f32_16x16x32_bf16 v[126:129], v[130:133], v[232:235], v[126:129]
	v_mfma_f32_16x16x32_bf16 v[122:125], v[138:141], v[232:235], v[122:125]
	v_mfma_f32_16x16x32_bf16 v[110:113], v[130:133], v[240:243], v[110:113]
	v_mfma_f32_16x16x32_bf16 v[106:109], v[138:141], v[240:243], v[106:109]
	v_mfma_f32_16x16x32_bf16 v[90:93], v[134:137], v[218:221], v[90:93]
	v_mfma_f32_16x16x32_bf16 v[74:77], v[142:145], v[218:221], v[74:77]
	v_mfma_f32_16x16x32_bf16 v[46:49], v[134:137], v[228:231], v[46:49]
	v_mfma_f32_16x16x32_bf16 v[42:45], v[142:145], v[228:231], v[42:45]
	v_mfma_f32_16x16x32_bf16 v[126:129], v[134:137], v[236:239], v[126:129]
	v_mfma_f32_16x16x32_bf16 v[122:125], v[142:145], v[236:239], v[122:125]
	v_mfma_f32_16x16x32_bf16 v[110:113], v[134:137], v[244:247], v[110:113]
	v_mfma_f32_16x16x32_bf16 v[106:109], v[142:145], v[244:247], v[106:109]
	s_setprio 0
	s_setprio 1
	v_mfma_f32_16x16x32_bf16 v[70:73], v[146:149], v[214:217], v[70:73]
	v_mfma_f32_16x16x32_bf16 v[66:69], v[176:179], v[214:217], v[66:69]
	v_mfma_f32_16x16x32_bf16 v[34:37], v[146:149], v[224:227], v[34:37]
	v_mfma_f32_16x16x32_bf16 v[38:41], v[176:179], v[224:227], v[38:41]
	v_mfma_f32_16x16x32_bf16 v[118:121], v[146:149], v[232:235], v[118:121]
	v_mfma_f32_16x16x32_bf16 v[114:117], v[176:179], v[232:235], v[114:117]
	v_mfma_f32_16x16x32_bf16 v[102:105], v[146:149], v[240:243], v[102:105]
	v_mfma_f32_16x16x32_bf16 v[98:101], v[176:179], v[240:243], v[98:101]
	v_mfma_f32_16x16x32_bf16 v[70:73], v[172:175], v[218:221], v[70:73]
	v_mfma_f32_16x16x32_bf16 v[66:69], v[210:213], v[218:221], v[66:69]
	v_mfma_f32_16x16x32_bf16 v[34:37], v[172:175], v[228:231], v[34:37]
	v_mfma_f32_16x16x32_bf16 v[38:41], v[210:213], v[228:231], v[38:41]
	v_mfma_f32_16x16x32_bf16 v[118:121], v[172:175], v[236:239], v[118:121]
	v_mfma_f32_16x16x32_bf16 v[114:117], v[210:213], v[236:239], v[114:117]
	v_mfma_f32_16x16x32_bf16 v[102:105], v[172:175], v[244:247], v[102:105]
	v_mfma_f32_16x16x32_bf16 v[98:101], v[210:213], v[244:247], v[98:101]
	s_barrier
	s_setprio 0
	s_add_i32 s17, s57, s46
	v_lshl_add_u64 v[180:181], s[10:11], 0, v[150:151]
	s_mov_b32 m0, s17
	ds_read_b128 v[214:217], v202 offset:16384
	ds_read_b128 v[218:221], v202 offset:17408
	ds_read_b128 v[224:227], v202 offset:18432
	ds_read_b128 v[228:231], v202 offset:19456
	ds_read_b128 v[232:235], v202 offset:20480
	ds_read_b128 v[236:239], v202 offset:21504
	ds_read_b128 v[240:243], v202 offset:22528
	ds_read_b128 v[244:247], v202 offset:23552
	global_load_lds_dwordx4 v[180:181], off
	s_add_i32 m0, s17, 0x2000
	s_add_u32 s18, s10, 0x2b0000
	v_lshl_add_u64 v[248:249], s[10:11], 0, v[152:153]
	s_addc_u32 s19, s11, 0
	s_add_i32 s17, s58, s46
	global_load_lds_dwordx4 v[248:249], off
	v_lshl_add_u64 v[250:251], s[18:19], 0, v[150:151]
	s_mov_b32 m0, s17
	v_lshl_add_u64 v[252:253], s[12:13], 0, v[152:153]
	global_load_lds_dwordx4 v[250:251], off
	v_lshl_add_u64 v[250:251], s[18:19], 0, v[152:153]
	s_add_i32 m0, s17, 0x2000
	s_nop 0
	global_load_lds_dwordx4 v[250:251], off
	v_lshl_add_u64 v[250:251], s[12:13], 0, v[150:151]
	s_mov_b32 m0, s48
	s_nop 0
	global_load_lds_dwordx4 v[250:251], off
	s_mov_b32 m0, s49
	s_nop 0
	global_load_lds_dwordx4 v[252:253], off
	s_waitcnt vmcnt(8)
	s_waitcnt lgkmcnt(0)
	s_setprio 1
	s_barrier
	v_mfma_f32_16x16x32_bf16 v[94:97], v[130:133], v[214:217], v[94:97]
	v_mfma_f32_16x16x32_bf16 v[86:89], v[138:141], v[214:217], v[86:89]
	v_mfma_f32_16x16x32_bf16 v[82:85], v[130:133], v[224:227], v[82:85]
	v_mfma_f32_16x16x32_bf16 v[78:81], v[138:141], v[224:227], v[78:81]
	v_mfma_f32_16x16x32_bf16 v[30:33], v[130:133], v[232:235], v[30:33]
	v_mfma_f32_16x16x32_bf16 v[26:29], v[138:141], v[232:235], v[26:29]
	v_mfma_f32_16x16x32_bf16 v[22:25], v[130:133], v[240:243], v[22:25]
	v_mfma_f32_16x16x32_bf16 v[18:21], v[138:141], v[240:243], v[18:21]
	v_mfma_f32_16x16x32_bf16 v[94:97], v[134:137], v[218:221], v[94:97]
	v_mfma_f32_16x16x32_bf16 v[86:89], v[142:145], v[218:221], v[86:89]
	v_mfma_f32_16x16x32_bf16 v[82:85], v[134:137], v[228:231], v[82:85]
	v_mfma_f32_16x16x32_bf16 v[78:81], v[142:145], v[228:231], v[78:81]
	v_mfma_f32_16x16x32_bf16 v[30:33], v[134:137], v[236:239], v[30:33]
	v_mfma_f32_16x16x32_bf16 v[26:29], v[142:145], v[236:239], v[26:29]
	v_mfma_f32_16x16x32_bf16 v[22:25], v[134:137], v[244:247], v[22:25]
	v_mfma_f32_16x16x32_bf16 v[18:21], v[142:145], v[244:247], v[18:21]
	s_setprio 0
	s_setprio 1
	v_mfma_f32_16x16x32_bf16 v[62:65], v[146:149], v[214:217], v[62:65]
	v_mfma_f32_16x16x32_bf16 v[58:61], v[176:179], v[214:217], v[58:61]
	v_mfma_f32_16x16x32_bf16 v[54:57], v[146:149], v[224:227], v[54:57]
	v_mfma_f32_16x16x32_bf16 v[50:53], v[176:179], v[224:227], v[50:53]
	v_mfma_f32_16x16x32_bf16 v[14:17], v[146:149], v[232:235], v[14:17]
	v_mfma_f32_16x16x32_bf16 v[6:9], v[176:179], v[232:235], v[6:9]
	v_mfma_f32_16x16x32_bf16 v[10:13], v[146:149], v[240:243], v[10:13]
	v_mfma_f32_16x16x32_bf16 v[2:5], v[176:179], v[240:243], v[2:5]
	v_mfma_f32_16x16x32_bf16 v[62:65], v[172:175], v[218:221], v[62:65]
	v_mfma_f32_16x16x32_bf16 v[58:61], v[210:213], v[218:221], v[58:61]
	v_mfma_f32_16x16x32_bf16 v[54:57], v[172:175], v[228:231], v[54:57]
	v_mfma_f32_16x16x32_bf16 v[50:53], v[210:213], v[228:231], v[50:53]
	v_mfma_f32_16x16x32_bf16 v[14:17], v[172:175], v[236:239], v[14:17]
	v_mfma_f32_16x16x32_bf16 v[6:9], v[210:213], v[236:239], v[6:9]
	v_mfma_f32_16x16x32_bf16 v[10:13], v[172:175], v[244:247], v[10:13]
	v_mfma_f32_16x16x32_bf16 v[2:5], v[210:213], v[244:247], v[2:5]
	s_barrier
	s_setprio 0
	s_add_i32 s17, 0, 0x18000
	s_add_i32 s18, 0, 0x1c000
	v_add_u32_e32 v142, s17, v182
	v_add_u32_e32 v154, s18, v182
	ds_read_b128 v[130:133], v142
	ds_read_b128 v[134:137], v142 offset:1024
	ds_read_b128 v[138:141], v142 offset:2048
	ds_read_b128 v[142:145], v142 offset:3072
	ds_read_b128 v[146:149], v154
	ds_read_b128 v[172:175], v154 offset:1024
	ds_read_b128 v[176:179], v154 offset:2048
	ds_read_b128 v[210:213], v154 offset:3072
	s_add_u32 s12, s12, 0x2b0000
	s_addc_u32 s13, s13, 0
	s_mov_b32 m0, s50
	v_lshl_add_u64 v[188:189], s[12:13], 0, v[150:151]
	ds_read_b128 v[214:217], v202 offset:32768
	ds_read_b128 v[218:221], v202 offset:33792
	ds_read_b128 v[224:227], v202 offset:34816
	ds_read_b128 v[228:231], v202 offset:35840
	ds_read_b128 v[232:235], v202 offset:36864
	ds_read_b128 v[236:239], v202 offset:37888
	ds_read_b128 v[240:243], v202 offset:38912
	ds_read_b128 v[244:247], v202 offset:39936
	global_load_lds_dwordx4 v[188:189], off
	v_lshl_add_u64 v[188:189], s[12:13], 0, v[152:153]
	s_mov_b32 m0, s51
	s_nop 0
	global_load_lds_dwordx4 v[188:189], off
	s_waitcnt vmcnt(8)
	s_waitcnt lgkmcnt(0)
	s_setprio 1
	s_barrier
	v_mfma_f32_16x16x32_bf16 v[90:93], v[130:133], v[214:217], v[90:93]
	v_mfma_f32_16x16x32_bf16 v[74:77], v[138:141], v[214:217], v[74:77]
	v_mfma_f32_16x16x32_bf16 v[46:49], v[130:133], v[224:227], v[46:49]
	v_mfma_f32_16x16x32_bf16 v[42:45], v[138:141], v[224:227], v[42:45]
	v_mfma_f32_16x16x32_bf16 v[126:129], v[130:133], v[232:235], v[126:129]
	v_mfma_f32_16x16x32_bf16 v[122:125], v[138:141], v[232:235], v[122:125]
	v_mfma_f32_16x16x32_bf16 v[110:113], v[130:133], v[240:243], v[110:113]
	v_mfma_f32_16x16x32_bf16 v[106:109], v[138:141], v[240:243], v[106:109]
	v_mfma_f32_16x16x32_bf16 v[90:93], v[134:137], v[218:221], v[90:93]
	v_mfma_f32_16x16x32_bf16 v[74:77], v[142:145], v[218:221], v[74:77]
	v_mfma_f32_16x16x32_bf16 v[46:49], v[134:137], v[228:231], v[46:49]
	v_mfma_f32_16x16x32_bf16 v[42:45], v[142:145], v[228:231], v[42:45]
	v_mfma_f32_16x16x32_bf16 v[126:129], v[134:137], v[236:239], v[126:129]
	v_mfma_f32_16x16x32_bf16 v[122:125], v[142:145], v[236:239], v[122:125]
	v_mfma_f32_16x16x32_bf16 v[110:113], v[134:137], v[244:247], v[110:113]
	v_mfma_f32_16x16x32_bf16 v[106:109], v[142:145], v[244:247], v[106:109]
	s_setprio 0
	s_setprio 1
	v_mfma_f32_16x16x32_bf16 v[70:73], v[146:149], v[214:217], v[70:73]
	v_mfma_f32_16x16x32_bf16 v[66:69], v[176:179], v[214:217], v[66:69]
	v_mfma_f32_16x16x32_bf16 v[34:37], v[146:149], v[224:227], v[34:37]
	v_mfma_f32_16x16x32_bf16 v[38:41], v[176:179], v[224:227], v[38:41]
	v_mfma_f32_16x16x32_bf16 v[118:121], v[146:149], v[232:235], v[118:121]
	v_mfma_f32_16x16x32_bf16 v[114:117], v[176:179], v[232:235], v[114:117]
	v_mfma_f32_16x16x32_bf16 v[102:105], v[146:149], v[240:243], v[102:105]
	v_mfma_f32_16x16x32_bf16 v[98:101], v[176:179], v[240:243], v[98:101]
	v_mfma_f32_16x16x32_bf16 v[70:73], v[172:175], v[218:221], v[70:73]
	v_mfma_f32_16x16x32_bf16 v[66:69], v[210:213], v[218:221], v[66:69]
	v_mfma_f32_16x16x32_bf16 v[34:37], v[172:175], v[228:231], v[34:37]
	v_mfma_f32_16x16x32_bf16 v[38:41], v[210:213], v[228:231], v[38:41]
	v_mfma_f32_16x16x32_bf16 v[118:121], v[172:175], v[236:239], v[118:121]
	v_mfma_f32_16x16x32_bf16 v[114:117], v[210:213], v[236:239], v[114:117]
	v_mfma_f32_16x16x32_bf16 v[102:105], v[172:175], v[244:247], v[102:105]
	v_mfma_f32_16x16x32_bf16 v[98:101], v[210:213], v[244:247], v[98:101]
	s_barrier
	s_setprio 0
	s_add_i32 s12, s17, s46
	v_lshl_add_u64 v[180:181], v[180:181], 0, s[30:31]
	s_mov_b32 m0, s12
	ds_read_b128 v[214:217], v202 offset:49152
	ds_read_b128 v[218:221], v202 offset:50176
	ds_read_b128 v[224:227], v202 offset:51200
	ds_read_b128 v[228:231], v202 offset:52224
	ds_read_b128 v[232:235], v202 offset:53248
	ds_read_b128 v[236:239], v202 offset:54272
	ds_read_b128 v[240:243], v202 offset:55296
	ds_read_b128 v[244:247], v202 offset:56320
	global_load_lds_dwordx4 v[180:181], off
	s_add_i32 m0, s12, 0x2000
	s_add_u32 s10, s10, 0x2b0080
	v_lshl_add_u64 v[180:181], v[248:249], 0, s[30:31]
	s_addc_u32 s11, s11, 0
	s_add_i32 s12, s18, s46
	global_load_lds_dwordx4 v[180:181], off
	v_lshl_add_u64 v[180:181], s[10:11], 0, v[150:151]
	s_mov_b32 m0, s12
	s_nop 0
	global_load_lds_dwordx4 v[180:181], off
	v_lshl_add_u64 v[180:181], s[10:11], 0, v[152:153]
	s_add_i32 m0, s12, 0x2000
	s_nop 0
	global_load_lds_dwordx4 v[180:181], off
	v_lshl_add_u64 v[180:181], v[250:251], 0, s[30:31]
	s_mov_b32 m0, s52
	s_nop 0
	global_load_lds_dwordx4 v[180:181], off
	v_lshl_add_u64 v[180:181], v[252:253], 0, s[30:31]
	s_mov_b32 m0, s53
	s_nop 0
	global_load_lds_dwordx4 v[180:181], off
	s_waitcnt vmcnt(8)
	s_waitcnt lgkmcnt(0)
	s_setprio 1
	s_barrier
	v_mfma_f32_16x16x32_bf16 v[94:97], v[130:133], v[214:217], v[94:97]
	v_mfma_f32_16x16x32_bf16 v[86:89], v[138:141], v[214:217], v[86:89]
	v_mfma_f32_16x16x32_bf16 v[82:85], v[130:133], v[224:227], v[82:85]
	v_mfma_f32_16x16x32_bf16 v[78:81], v[138:141], v[224:227], v[78:81]
	v_mfma_f32_16x16x32_bf16 v[30:33], v[130:133], v[232:235], v[30:33]
	v_mfma_f32_16x16x32_bf16 v[26:29], v[138:141], v[232:235], v[26:29]
	v_mfma_f32_16x16x32_bf16 v[22:25], v[130:133], v[240:243], v[22:25]
	v_mfma_f32_16x16x32_bf16 v[18:21], v[138:141], v[240:243], v[18:21]
	v_mfma_f32_16x16x32_bf16 v[94:97], v[134:137], v[218:221], v[94:97]
	v_mfma_f32_16x16x32_bf16 v[86:89], v[142:145], v[218:221], v[86:89]
	v_mfma_f32_16x16x32_bf16 v[82:85], v[134:137], v[228:231], v[82:85]
	v_mfma_f32_16x16x32_bf16 v[78:81], v[142:145], v[228:231], v[78:81]
	v_mfma_f32_16x16x32_bf16 v[30:33], v[134:137], v[236:239], v[30:33]
	v_mfma_f32_16x16x32_bf16 v[26:29], v[142:145], v[236:239], v[26:29]
	v_mfma_f32_16x16x32_bf16 v[22:25], v[134:137], v[244:247], v[22:25]
	v_mfma_f32_16x16x32_bf16 v[18:21], v[142:145], v[244:247], v[18:21]
	s_setprio 0
	s_setprio 1
	v_mfma_f32_16x16x32_bf16 v[62:65], v[146:149], v[214:217], v[62:65]
	v_mfma_f32_16x16x32_bf16 v[58:61], v[176:179], v[214:217], v[58:61]
	v_mfma_f32_16x16x32_bf16 v[54:57], v[146:149], v[224:227], v[54:57]
	v_mfma_f32_16x16x32_bf16 v[50:53], v[176:179], v[224:227], v[50:53]
	v_mfma_f32_16x16x32_bf16 v[14:17], v[146:149], v[232:235], v[14:17]
	v_mfma_f32_16x16x32_bf16 v[6:9], v[176:179], v[232:235], v[6:9]
	v_mfma_f32_16x16x32_bf16 v[10:13], v[146:149], v[240:243], v[10:13]
	v_mfma_f32_16x16x32_bf16 v[2:5], v[176:179], v[240:243], v[2:5]
	v_mfma_f32_16x16x32_bf16 v[62:65], v[172:175], v[218:221], v[62:65]
	v_mfma_f32_16x16x32_bf16 v[58:61], v[210:213], v[218:221], v[58:61]
	v_mfma_f32_16x16x32_bf16 v[54:57], v[172:175], v[228:231], v[54:57]
	v_mfma_f32_16x16x32_bf16 v[50:53], v[210:213], v[228:231], v[50:53]
	v_mfma_f32_16x16x32_bf16 v[14:17], v[172:175], v[236:239], v[14:17]
	v_mfma_f32_16x16x32_bf16 v[6:9], v[210:213], v[236:239], v[6:9]
	v_mfma_f32_16x16x32_bf16 v[10:13], v[172:175], v[244:247], v[10:13]
	v_mfma_f32_16x16x32_bf16 v[2:5], v[210:213], v[244:247], v[2:5]
	s_barrier
	s_setprio 0
	s_add_i32 s16, s16, 2
	s_add_u32 s8, s8, 0x100
	s_addc_u32 s9, s9, 0
	s_add_u32 s14, s14, 0x100
	s_addc_u32 s15, s15, 0
	s_cmpk_gt_u32 s16, 0xa9
	s_cbranch_scc0 .LBB0_1040
	s_and_b64 vcc, exec, s[34:35]
	s_cbranch_vccz .LBB0_1043
	s_barrier

	.amdhsa_kernel _Z6mk_fwd4Args
		.amdhsa_group_segment_fixed_size 0
		.amdhsa_private_segment_fixed_size 0
		.amdhsa_kernarg_size 432
		.amdhsa_user_sgpr_count 2
		.amdhsa_user_sgpr_dispatch_ptr 0
		.amdhsa_user_sgpr_queue_ptr 0
		.amdhsa_user_sgpr_kernarg_segment_ptr 1
		.amdhsa_user_sgpr_dispatch_id 0
		.amdhsa_user_sgpr_kernarg_preload_length 0
		.amdhsa_user_sgpr_kernarg_preload_offset 0
		.amdhsa_user_sgpr_private_segment_size 0
		.amdhsa_uses_dynamic_stack 0
		.amdhsa_enable_private_segment 0
		.amdhsa_system_sgpr_workgroup_id_x 1
		.amdhsa_system_sgpr_workgroup_id_y 0
		.amdhsa_system_sgpr_workgroup_id_z 0
		.amdhsa_system_sgpr_workgroup_info 0
		.amdhsa_system_vgpr_workitem_id 0
		.amdhsa_next_free_vgpr 256
		.amdhsa_next_free_sgpr 100
		.amdhsa_accum_offset 256
		.amdhsa_reserve_vcc 1
		.amdhsa_float_round_mode_32 0
		.amdhsa_float_round_mode_16_64 0
		.amdhsa_float_denorm_mode_32 3
		.amdhsa_float_denorm_mode_16_64 3
		.amdhsa_dx10_clamp 1
		.amdhsa_ieee_mode 1
		.amdhsa_fp16_overflow 0
		.amdhsa_tg_split 0
		.amdhsa_exception_fp_ieee_invalid_op 0
		.amdhsa_exception_fp_denorm_src 0
		.amdhsa_exception_fp_ieee_div_zero 0
		.amdhsa_exception_fp_ieee_overflow 0
		.amdhsa_exception_fp_ieee_underflow 0
		.amdhsa_exception_fp_ieee_inexact 0
		.amdhsa_exception_int_div_zero 0
	.end_amdhsa_kernel

amdhsa.kernels:
  - .agpr_count:     0
    .args:
      - .offset:         0
        .size:           176
        .value_kind:     by_value
      - .offset:         176
        .size:           4
        .value_kind:     hidden_block_count_x
      - .offset:         180
        .size:           4
        .value_kind:     hidden_block_count_y
      - .offset:         184
        .size:           4
        .value_kind:     hidden_block_count_z
      - .offset:         188
        .size:           2
        .value_kind:     hidden_group_size_x
      - .offset:         190
        .size:           2
        .value_kind:     hidden_group_size_y
      - .offset:         192
        .size:           2
        .value_kind:     hidden_group_size_z
      - .offset:         194
        .size:           2
        .value_kind:     hidden_remainder_x
      - .offset:         196
        .size:           2
        .value_kind:     hidden_remainder_y
      - .offset:         198
        .size:           2
        .value_kind:     hidden_remainder_z
      - .offset:         216
        .size:           8
        .value_kind:     hidden_global_offset_x
      - .offset:         224
        .size:           8
        .value_kind:     hidden_global_offset_y
      - .offset:         232
        .size:           8
        .value_kind:     hidden_global_offset_z
      - .offset:         240
        .size:           2
        .value_kind:     hidden_grid_dims
      - .offset:         296
        .size:           4
        .value_kind:     hidden_dynamic_lds_size
    .group_segment_fixed_size: 0
    .kernarg_segment_align: 8
    .kernarg_segment_size: 432
    .language:       OpenCL C
    .language_version:
      - 2
      - 0
    .max_flat_workgroup_size: 512
    .name:           _Z6mk_fwd4Args
    .private_segment_fixed_size: 0
    .sgpr_count:     106
    .sgpr_spill_count: 27
    .symbol:         _Z6mk_fwd4Args.kd
    .uniform_work_group_size: 1
    .uses_dynamic_stack: false
    .vgpr_count:     256
    .vgpr_spill_count: 0
    .wavefront_size: 64
